# GEMM mainloops: LDS-DMA addresses via scalar base + constant lane offset (no 64-bit VALU adds in the loops); attention tile loop software-pipelined
# speedup vs baseline: 1.0192x; 1.0017x over previous
; #define PG8_STAGE(bufoff, gbase, voff) do { _Pragma("unroll") for (int _i = 0; _i < 2; ++_i) \
;         __builtin_amdgcn_global_load_lds((const unsigned*)((const char*)(gbase) + (voff)[_i]), (PG8_LAS unsigned*)(lds + (bufoff) + ldsw + _i * 8192), 16, 0, 0); } while (0)
; #define PG8_LDA(dst, b, h) do { _Pragma("unroll") for (int m = 0; m < 4; ++m) _Pragma("unroll") for (int k = 0; k < 2; ++k) dst[m][k] = *(const PG8_LAS bf16x8*)(lds + PG8_SA(b, h) + aoff + m * 2048 + k * 1024); } while (0)
; #define PG8_LDB(dst, b, h) do { _Pragma("unroll") for (int n = 0; n < 2; ++n) _Pragma("unroll") for (int k = 0; k < 2; ++k) dst[n][k] = *(const PG8_LAS bf16x8*)(lds + PG8_SB(b, h) + boff + n * 2048 + k * 1024); } while (0)
; #define PG8_MMA(ai, bj, At, Bt) do { __builtin_amdgcn_s_setprio(1); _Pragma("unroll") for (int m = 0; m < 4; ++m) _Pragma("unroll") for (int n = 0; n < 2; ++n) _Pragma("unroll") for (int k = 0; k < 2; ++k) \
;         acc[ai][bj][m][n] = __builtin_amdgcn_mfma_f32_16x16x32_bf16(Bt[n][k], At[m][k], acc[ai][bj][m][n], 0, 0, 0); __builtin_amdgcn_s_setprio(0); } while (0)
; #define PG8_WAIT_V(n) asm volatile("s_waitcnt vmcnt(" #n ")" ::: "memory")
; #define PG8_WAIT_L(n) asm volatile("s_waitcnt lgkmcnt(" #n ")" ::: "memory")
; template <class Epi, class Sched, bool ALIGN_EPI = false, bool SP2 = false>
; __device__ __forceinline__ void gemm_phase(PG8_LAS unsigned char* lds, const Gemm g, const Sched& S, const Epi& E) {
;     ...
;             const bool last = (t == nt - 2);
;             const char* a1 = cA + (size_t)(t + 1) * kstep;
;             const char* a2 = last ? nA : cA + (size_t)(t + 2) * kstep; const char* b2 = last ? nB : cB + (size_t)(t + 2) * kstep;
;             const char* a3 = a2 + kstep; const char* b3 = b2 + kstep;
;             if (last && has_next) S.a_ready(nxt);
;             if constexpr (SP2) {
;             PG8_LDB(B0, 0, 0); PG8_LDB(B1, 0, 1); PG8_SCHED; PG8_LDA(At, 0, 0); PG8_STAGE(PG8_SA(1, 1), a1 + hstep, voffA);
;             PG8_WAIT_V(8); PG8_WAIT_L(0); PG8_BAR; PG8_MMA(0, 0, At, B0); PG8_MMA(0, 1, At, B1); PG8_BAR; PG8_SCHED;
;             PG8_LDA(At, 0, 1); PG8_STAGE(PG8_SB(0, 0), b2, voffB); PG8_STAGE(PG8_SB(0, 1), b2 + hstep, voffB); PG8_STAGE(PG8_SA(0, 0), a2, voffA);
;             PG8_WAIT_V(8); PG8_WAIT_L(0); PG8_BAR; PG8_MMA(1, 0, At, B0); PG8_MMA(1, 1, At, B1); PG8_BAR; PG8_SCHED;
.LBB0_343:
	ds_read_b128 v[128:131], v185
	ds_read_b128 v[132:135], v185 offset:1024
	ds_read_b128 v[136:139], v185 offset:2048
	ds_read_b128 v[140:143], v185 offset:3072
	ds_read_b128 v[172:175], v186
	ds_read_b128 v[176:179], v186 offset:1024
	ds_read_b128 v[180:183], v186 offset:2048
	ds_read_b128 v[192:195], v186 offset:3072
	s_add_u32 s0, s78, 0xfffc0080
	s_addc_u32 s1, s79, -1
	s_cmp_eq_u32 s30, 12
	s_cselect_b32 s83, s53, s1
	s_cselect_b32 s82, vcc_lo, s0
	s_cselect_b32 s81, s55, s3
	s_cselect_b32 s80, vcc_hi, s84
	s_add_i32 m0, s92, 0xc000
	ds_read_b128 v[196:199], v187
	ds_read_b128 v[200:203], v187 offset:1024
	ds_read_b128 v[204:207], v187 offset:2048
	ds_read_b128 v[208:211], v187 offset:3072
	ds_read_b128 v[212:215], v187 offset:4096
	ds_read_b128 v[216:219], v187 offset:5120
	ds_read_b128 v[220:223], v187 offset:6144
	ds_read_b128 v[224:227], v187 offset:7168
	global_load_lds_dwordx4 v162, s[78:79]
	s_add_i32 m0, s92, 0xe000
	s_nop 0
	global_load_lds_dwordx4 v166, s[78:79]
	s_waitcnt vmcnt(8)
	s_waitcnt lgkmcnt(0)
	s_barrier
	s_setprio 1
	s_waitcnt lgkmcnt(0)
	v_mfma_f32_16x16x32_bf16 v[124:127], v[128:131], v[196:199], v[124:127]
	v_mfma_f32_16x16x32_bf16 v[120:123], v[136:139], v[196:199], v[120:123]
	v_mfma_f32_16x16x32_bf16 v[116:119], v[128:131], v[204:207], v[116:119]
	v_mfma_f32_16x16x32_bf16 v[112:115], v[136:139], v[204:207], v[112:115]
	v_mfma_f32_16x16x32_bf16 v[100:103], v[128:131], v[212:215], v[100:103]
	v_mfma_f32_16x16x32_bf16 v[96:99], v[136:139], v[212:215], v[96:99]
	v_mfma_f32_16x16x32_bf16 v[84:87], v[128:131], v[220:223], v[84:87]
	v_mfma_f32_16x16x32_bf16 v[80:83], v[136:139], v[220:223], v[80:83]
	v_mfma_f32_16x16x32_bf16 v[124:127], v[132:135], v[200:203], v[124:127]
	v_mfma_f32_16x16x32_bf16 v[120:123], v[140:143], v[200:203], v[120:123]
	v_mfma_f32_16x16x32_bf16 v[116:119], v[132:135], v[208:211], v[116:119]
	v_mfma_f32_16x16x32_bf16 v[112:115], v[140:143], v[208:211], v[112:115]
	v_mfma_f32_16x16x32_bf16 v[100:103], v[132:135], v[216:219], v[100:103]
	v_mfma_f32_16x16x32_bf16 v[96:99], v[140:143], v[216:219], v[96:99]
	v_mfma_f32_16x16x32_bf16 v[84:87], v[132:135], v[224:227], v[84:87]
	v_mfma_f32_16x16x32_bf16 v[80:83], v[140:143], v[224:227], v[80:83]
	s_setprio 0
	s_setprio 1
	v_mfma_f32_16x16x32_bf16 v[108:111], v[172:175], v[196:199], v[108:111]
	v_mfma_f32_16x16x32_bf16 v[104:107], v[180:183], v[196:199], v[104:107]
	v_mfma_f32_16x16x32_bf16 v[92:95], v[172:175], v[204:207], v[92:95]
	v_mfma_f32_16x16x32_bf16 v[88:91], v[180:183], v[204:207], v[88:91]
	v_mfma_f32_16x16x32_bf16 v[76:79], v[172:175], v[212:215], v[76:79]
	v_mfma_f32_16x16x32_bf16 v[72:75], v[180:183], v[212:215], v[72:75]
	v_mfma_f32_16x16x32_bf16 v[68:71], v[172:175], v[220:223], v[68:71]
	v_mfma_f32_16x16x32_bf16 v[64:67], v[180:183], v[220:223], v[64:67]
	v_mfma_f32_16x16x32_bf16 v[108:111], v[176:179], v[200:203], v[108:111]
	v_mfma_f32_16x16x32_bf16 v[104:107], v[192:195], v[200:203], v[104:107]
	v_mfma_f32_16x16x32_bf16 v[92:95], v[176:179], v[208:211], v[92:95]
	v_mfma_f32_16x16x32_bf16 v[88:91], v[192:195], v[208:211], v[88:91]
	v_mfma_f32_16x16x32_bf16 v[76:79], v[176:179], v[216:219], v[76:79]
	v_mfma_f32_16x16x32_bf16 v[72:75], v[192:195], v[216:219], v[72:75]
	v_mfma_f32_16x16x32_bf16 v[68:71], v[176:179], v[224:227], v[68:71]
	v_mfma_f32_16x16x32_bf16 v[64:67], v[192:195], v[224:227], v[64:67]
	s_setprio 0
	s_barrier
	s_add_i32 s0, s8, s51
	s_mov_b32 m0, s0
	ds_read_b128 v[196:199], v187 offset:16384
	ds_read_b128 v[200:203], v187 offset:17408
	ds_read_b128 v[204:207], v187 offset:18432
	ds_read_b128 v[208:211], v187 offset:19456
	ds_read_b128 v[212:215], v187 offset:20480
	ds_read_b128 v[216:219], v187 offset:21504
	ds_read_b128 v[220:223], v187 offset:22528
	ds_read_b128 v[224:227], v187 offset:23552
	global_load_lds_dwordx4 v150, s[80:81]
	s_add_i32 m0, s0, 0x2000
	s_add_u32 s0, s80, 0x40000
	s_addc_u32 s1, s81, 0
	s_add_i32 s31, s9, s51
	global_load_lds_dwordx4 v146, s[80:81]
	s_mov_b32 m0, s31
	s_nop 0
	global_load_lds_dwordx4 v150, s[0:1]
	s_add_i32 m0, s31, 0x2000
	s_nop 0
	global_load_lds_dwordx4 v146, s[0:1]
	s_mov_b32 m0, s92
	s_nop 0
	global_load_lds_dwordx4 v152, s[82:83]
	s_mov_b32 m0, s93
	s_nop 0
	global_load_lds_dwordx4 v148, s[82:83]
	s_waitcnt vmcnt(8)
	s_waitcnt lgkmcnt(0)
	s_barrier
	s_setprio 1
	s_waitcnt lgkmcnt(0)
	v_mfma_f32_16x16x32_bf16 v[60:63], v[128:131], v[196:199], v[60:63]
	v_mfma_f32_16x16x32_bf16 v[56:59], v[136:139], v[196:199], v[56:59]
	v_mfma_f32_16x16x32_bf16 v[52:55], v[128:131], v[204:207], v[52:55]
	v_mfma_f32_16x16x32_bf16 v[48:51], v[136:139], v[204:207], v[48:51]
	v_mfma_f32_16x16x32_bf16 v[36:39], v[128:131], v[212:215], v[36:39]
	v_mfma_f32_16x16x32_bf16 v[32:35], v[136:139], v[212:215], v[32:35]
	v_mfma_f32_16x16x32_bf16 v[20:23], v[128:131], v[220:223], v[20:23]
	v_mfma_f32_16x16x32_bf16 v[16:19], v[136:139], v[220:223], v[16:19]
	v_mfma_f32_16x16x32_bf16 v[60:63], v[132:135], v[200:203], v[60:63]
	v_mfma_f32_16x16x32_bf16 v[56:59], v[140:143], v[200:203], v[56:59]
	v_mfma_f32_16x16x32_bf16 v[52:55], v[132:135], v[208:211], v[52:55]
	v_mfma_f32_16x16x32_bf16 v[48:51], v[140:143], v[208:211], v[48:51]
	v_mfma_f32_16x16x32_bf16 v[36:39], v[132:135], v[216:219], v[36:39]
	v_mfma_f32_16x16x32_bf16 v[32:35], v[140:143], v[216:219], v[32:35]
	v_mfma_f32_16x16x32_bf16 v[20:23], v[132:135], v[224:227], v[20:23]
	v_mfma_f32_16x16x32_bf16 v[16:19], v[140:143], v[224:227], v[16:19]
	s_setprio 0
	s_setprio 1
	v_mfma_f32_16x16x32_bf16 v[44:47], v[172:175], v[196:199], v[44:47]
	v_mfma_f32_16x16x32_bf16 v[40:43], v[180:183], v[196:199], v[40:43]
	v_mfma_f32_16x16x32_bf16 v[28:31], v[172:175], v[204:207], v[28:31]
	v_mfma_f32_16x16x32_bf16 v[24:27], v[180:183], v[204:207], v[24:27]
	v_mfma_f32_16x16x32_bf16 v[12:15], v[172:175], v[212:215], v[12:15]
	v_mfma_f32_16x16x32_bf16 v[8:11], v[180:183], v[212:215], v[8:11]
	v_mfma_f32_16x16x32_bf16 v[4:7], v[172:175], v[220:223], v[4:7]
	v_mfma_f32_16x16x32_bf16 v[0:3], v[180:183], v[220:223], v[0:3]
	v_mfma_f32_16x16x32_bf16 v[44:47], v[176:179], v[200:203], v[44:47]
	v_mfma_f32_16x16x32_bf16 v[40:43], v[192:195], v[200:203], v[40:43]
	v_mfma_f32_16x16x32_bf16 v[28:31], v[176:179], v[208:211], v[28:31]
	v_mfma_f32_16x16x32_bf16 v[24:27], v[192:195], v[208:211], v[24:27]
	v_mfma_f32_16x16x32_bf16 v[12:15], v[176:179], v[216:219], v[12:15]
	v_mfma_f32_16x16x32_bf16 v[8:11], v[192:195], v[216:219], v[8:11]
	v_mfma_f32_16x16x32_bf16 v[4:7], v[176:179], v[224:227], v[4:7]
	v_mfma_f32_16x16x32_bf16 v[0:3], v[192:195], v[224:227], v[0:3]
	s_setprio 0
	s_barrier
; #define PG8_STAGE(bufoff, gbase, voff) do { _Pragma("unroll") for (int _i = 0; _i < 2; ++_i) \
;         __builtin_amdgcn_global_load_lds((const unsigned*)((const char*)(gbase) + (voff)[_i]), (PG8_LAS unsigned*)(lds + (bufoff) + ldsw + _i * 8192), 16, 0, 0); } while (0)
; #define PG8_LDA(dst, b, h) do { _Pragma("unroll") for (int m = 0; m < 4; ++m) _Pragma("unroll") for (int k = 0; k < 2; ++k) dst[m][k] = *(const PG8_LAS bf16x8*)(lds + PG8_SA(b, h) + aoff + m * 2048 + k * 1024); } while (0)
; #define PG8_LDB(dst, b, h) do { _Pragma("unroll") for (int n = 0; n < 2; ++n) _Pragma("unroll") for (int k = 0; k < 2; ++k) dst[n][k] = *(const PG8_LAS bf16x8*)(lds + PG8_SB(b, h) + boff + n * 2048 + k * 1024); } while (0)
; #define PG8_MMA(ai, bj, At, Bt) do { __builtin_amdgcn_s_setprio(1); _Pragma("unroll") for (int m = 0; m < 4; ++m) _Pragma("unroll") for (int n = 0; n < 2; ++n) _Pragma("unroll") for (int k = 0; k < 2; ++k) \
;         acc[ai][bj][m][n] = __builtin_amdgcn_mfma_f32_16x16x32_bf16(Bt[n][k], At[m][k], acc[ai][bj][m][n], 0, 0, 0); __builtin_amdgcn_s_setprio(0); } while (0)
; #define PG8_WAIT_V(n) asm volatile("s_waitcnt vmcnt(" #n ")" ::: "memory")
; #define PG8_WAIT_L(n) asm volatile("s_waitcnt lgkmcnt(" #n ")" ::: "memory")
; #define PG8_BAR __builtin_amdgcn_s_barrier()
; #define PG8_SCHED __builtin_amdgcn_sched_barrier(0)
; template <class Epi, class Sched, bool ALIGN_EPI = false, bool SP2 = false>
; __device__ __forceinline__ void gemm_phase(PG8_LAS unsigned char* lds, const Gemm g, const Sched& S, const Epi& E) {
;     ...
;             PG8_LDB(B0, 1, 0); PG8_LDB(B1, 1, 1); PG8_SCHED; PG8_LDA(At, 1, 0); PG8_STAGE(PG8_SA(0, 1), a2 + hstep, voffA);
;             PG8_WAIT_V(8); PG8_WAIT_L(0); PG8_BAR; PG8_MMA(0, 0, At, B0); PG8_MMA(0, 1, At, B1); PG8_BAR; PG8_SCHED;
;             PG8_LDA(At, 1, 1); PG8_STAGE(PG8_SB(1, 0), b3, voffB); PG8_STAGE(PG8_SB(1, 1), b3 + hstep, voffB); PG8_STAGE(PG8_SA(1, 0), a3, voffA);
;             PG8_WAIT_V(8); PG8_WAIT_L(0); PG8_BAR; PG8_MMA(1, 0, At, B0); PG8_MMA(1, 1, At, B1); PG8_BAR; PG8_SCHED;
	s_add_i32 s31, 0, 0x18000
	s_add_i32 s91, 0, 0x1c000
	v_add_u32_e32 v140, s31, v157
	v_add_u32_e32 v154, s91, v157
	ds_read_b128 v[128:131], v140
	ds_read_b128 v[132:135], v140 offset:1024
	ds_read_b128 v[136:139], v140 offset:2048
	ds_read_b128 v[140:143], v140 offset:3072
	ds_read_b128 v[172:175], v154
	ds_read_b128 v[176:179], v154 offset:1024
	ds_read_b128 v[180:183], v154 offset:2048
	ds_read_b128 v[192:195], v154 offset:3072
	s_add_u32 s0, s82, 0x40000
	s_addc_u32 s1, s83, 0
	s_mov_b32 m0, s94
	ds_read_b128 v[196:199], v187 offset:32768
	ds_read_b128 v[200:203], v187 offset:33792
	ds_read_b128 v[204:207], v187 offset:34816
	ds_read_b128 v[208:211], v187 offset:35840
	ds_read_b128 v[212:215], v187 offset:36864
	ds_read_b128 v[216:219], v187 offset:37888
	ds_read_b128 v[220:223], v187 offset:38912
	ds_read_b128 v[224:227], v187 offset:39936
	global_load_lds_dwordx4 v152, s[0:1]
	s_mov_b32 m0, s95
	s_nop 0
	global_load_lds_dwordx4 v148, s[0:1]
	s_add_u32 s100, s80, 0x80
	s_addc_u32 s101, s81, 0
	s_add_u32 s98, s82, 0x80
	s_addc_u32 s99, s83, 0
	s_waitcnt vmcnt(8)
	s_waitcnt lgkmcnt(0)
	s_barrier
	s_setprio 1
	s_waitcnt lgkmcnt(0)
	v_mfma_f32_16x16x32_bf16 v[124:127], v[128:131], v[196:199], v[124:127]
	v_mfma_f32_16x16x32_bf16 v[120:123], v[136:139], v[196:199], v[120:123]
	v_mfma_f32_16x16x32_bf16 v[116:119], v[128:131], v[204:207], v[116:119]
	v_mfma_f32_16x16x32_bf16 v[112:115], v[136:139], v[204:207], v[112:115]
	v_mfma_f32_16x16x32_bf16 v[100:103], v[128:131], v[212:215], v[100:103]
	v_mfma_f32_16x16x32_bf16 v[96:99], v[136:139], v[212:215], v[96:99]
	v_mfma_f32_16x16x32_bf16 v[84:87], v[128:131], v[220:223], v[84:87]
	v_mfma_f32_16x16x32_bf16 v[80:83], v[136:139], v[220:223], v[80:83]
	v_mfma_f32_16x16x32_bf16 v[124:127], v[132:135], v[200:203], v[124:127]
	v_mfma_f32_16x16x32_bf16 v[120:123], v[140:143], v[200:203], v[120:123]
	v_mfma_f32_16x16x32_bf16 v[116:119], v[132:135], v[208:211], v[116:119]
	v_mfma_f32_16x16x32_bf16 v[112:115], v[140:143], v[208:211], v[112:115]
	v_mfma_f32_16x16x32_bf16 v[100:103], v[132:135], v[216:219], v[100:103]
	v_mfma_f32_16x16x32_bf16 v[96:99], v[140:143], v[216:219], v[96:99]
	v_mfma_f32_16x16x32_bf16 v[84:87], v[132:135], v[224:227], v[84:87]
	v_mfma_f32_16x16x32_bf16 v[80:83], v[140:143], v[224:227], v[80:83]
	s_setprio 0
	s_setprio 1
	v_mfma_f32_16x16x32_bf16 v[108:111], v[172:175], v[196:199], v[108:111]
	v_mfma_f32_16x16x32_bf16 v[104:107], v[180:183], v[196:199], v[104:107]
	v_mfma_f32_16x16x32_bf16 v[92:95], v[172:175], v[204:207], v[92:95]
	v_mfma_f32_16x16x32_bf16 v[88:91], v[180:183], v[204:207], v[88:91]
	v_mfma_f32_16x16x32_bf16 v[76:79], v[172:175], v[212:215], v[76:79]
	v_mfma_f32_16x16x32_bf16 v[72:75], v[180:183], v[212:215], v[72:75]
	v_mfma_f32_16x16x32_bf16 v[68:71], v[172:175], v[220:223], v[68:71]
	v_mfma_f32_16x16x32_bf16 v[64:67], v[180:183], v[220:223], v[64:67]
	v_mfma_f32_16x16x32_bf16 v[108:111], v[176:179], v[200:203], v[108:111]
	v_mfma_f32_16x16x32_bf16 v[104:107], v[192:195], v[200:203], v[104:107]
	v_mfma_f32_16x16x32_bf16 v[92:95], v[176:179], v[208:211], v[92:95]
	v_mfma_f32_16x16x32_bf16 v[88:91], v[192:195], v[208:211], v[88:91]
	v_mfma_f32_16x16x32_bf16 v[76:79], v[176:179], v[216:219], v[76:79]
	v_mfma_f32_16x16x32_bf16 v[72:75], v[192:195], v[216:219], v[72:75]
	v_mfma_f32_16x16x32_bf16 v[68:71], v[176:179], v[224:227], v[68:71]
	v_mfma_f32_16x16x32_bf16 v[64:67], v[192:195], v[224:227], v[64:67]
	s_setprio 0
	s_barrier
	s_add_i32 s0, s31, s51
	s_mov_b32 m0, s0
	ds_read_b128 v[196:199], v187 offset:49152
	ds_read_b128 v[200:203], v187 offset:50176
	ds_read_b128 v[204:207], v187 offset:51200
	ds_read_b128 v[208:211], v187 offset:52224
	ds_read_b128 v[212:215], v187 offset:53248
	ds_read_b128 v[216:219], v187 offset:54272
	ds_read_b128 v[220:223], v187 offset:55296
	ds_read_b128 v[224:227], v187 offset:56320
	global_load_lds_dwordx4 v150, s[100:101]
	s_add_i32 m0, s0, 0x2000
	s_add_u32 s0, s80, 0x40080
	s_addc_u32 s1, s81, 0
	s_add_i32 s31, s91, s51
	global_load_lds_dwordx4 v146, s[100:101]
	s_mov_b32 m0, s31
	s_nop 0
	global_load_lds_dwordx4 v150, s[0:1]
	s_add_i32 m0, s31, 0x2000
	s_nop 0
	global_load_lds_dwordx4 v146, s[0:1]
	s_mov_b32 m0, s97
	s_nop 0
	global_load_lds_dwordx4 v152, s[98:99]
	s_mov_b32 m0, s34
	s_nop 0
	global_load_lds_dwordx4 v148, s[98:99]
	s_waitcnt vmcnt(8)
	s_waitcnt lgkmcnt(0)
	s_barrier
	s_setprio 1
	s_waitcnt lgkmcnt(0)
	v_mfma_f32_16x16x32_bf16 v[60:63], v[128:131], v[196:199], v[60:63]
	v_mfma_f32_16x16x32_bf16 v[56:59], v[136:139], v[196:199], v[56:59]
	v_mfma_f32_16x16x32_bf16 v[52:55], v[128:131], v[204:207], v[52:55]
	v_mfma_f32_16x16x32_bf16 v[48:51], v[136:139], v[204:207], v[48:51]
	v_mfma_f32_16x16x32_bf16 v[36:39], v[128:131], v[212:215], v[36:39]
	v_mfma_f32_16x16x32_bf16 v[32:35], v[136:139], v[212:215], v[32:35]
	v_mfma_f32_16x16x32_bf16 v[20:23], v[128:131], v[220:223], v[20:23]
	v_mfma_f32_16x16x32_bf16 v[16:19], v[136:139], v[220:223], v[16:19]
	v_mfma_f32_16x16x32_bf16 v[60:63], v[132:135], v[200:203], v[60:63]
	v_mfma_f32_16x16x32_bf16 v[56:59], v[140:143], v[200:203], v[56:59]
	v_mfma_f32_16x16x32_bf16 v[52:55], v[132:135], v[208:211], v[52:55]
	v_mfma_f32_16x16x32_bf16 v[48:51], v[140:143], v[208:211], v[48:51]
	v_mfma_f32_16x16x32_bf16 v[36:39], v[132:135], v[216:219], v[36:39]
	v_mfma_f32_16x16x32_bf16 v[32:35], v[140:143], v[216:219], v[32:35]
	v_mfma_f32_16x16x32_bf16 v[20:23], v[132:135], v[224:227], v[20:23]
	v_mfma_f32_16x16x32_bf16 v[16:19], v[140:143], v[224:227], v[16:19]
	s_setprio 0
	s_setprio 1
	v_mfma_f32_16x16x32_bf16 v[44:47], v[172:175], v[196:199], v[44:47]
	v_mfma_f32_16x16x32_bf16 v[40:43], v[180:183], v[196:199], v[40:43]
	v_mfma_f32_16x16x32_bf16 v[28:31], v[172:175], v[204:207], v[28:31]
	v_mfma_f32_16x16x32_bf16 v[24:27], v[180:183], v[204:207], v[24:27]
	v_mfma_f32_16x16x32_bf16 v[12:15], v[172:175], v[212:215], v[12:15]
	v_mfma_f32_16x16x32_bf16 v[8:11], v[180:183], v[212:215], v[8:11]
	v_mfma_f32_16x16x32_bf16 v[4:7], v[172:175], v[220:223], v[4:7]
	v_mfma_f32_16x16x32_bf16 v[0:3], v[180:183], v[220:223], v[0:3]
	v_mfma_f32_16x16x32_bf16 v[44:47], v[176:179], v[200:203], v[44:47]
	v_mfma_f32_16x16x32_bf16 v[40:43], v[192:195], v[200:203], v[40:43]
	v_mfma_f32_16x16x32_bf16 v[28:31], v[176:179], v[208:211], v[28:31]
	v_mfma_f32_16x16x32_bf16 v[24:27], v[192:195], v[208:211], v[24:27]
	v_mfma_f32_16x16x32_bf16 v[12:15], v[176:179], v[216:219], v[12:15]
	v_mfma_f32_16x16x32_bf16 v[8:11], v[192:195], v[216:219], v[8:11]
	v_mfma_f32_16x16x32_bf16 v[4:7], v[176:179], v[224:227], v[4:7]
	v_mfma_f32_16x16x32_bf16 v[0:3], v[192:195], v[224:227], v[0:3]
	s_setprio 0
	s_barrier
	s_add_i32 s30, s30, 2
	s_add_u32 s78, s78, 0x100
	s_addc_u32 s79, s79, 0
	s_add_u32 s84, s84, 0x100
	s_addc_u32 s3, s3, 0
	s_cmp_gt_u32 s30, 13
	s_cbranch_scc0 .LBB0_343
	s_and_b64 vcc, exec, s[48:49]
	s_cbranch_vccz .LBB0_346
	s_barrier

; #define PG8_STAGE(bufoff, gbase, voff) do { _Pragma("unroll") for (int _i = 0; _i < 2; ++_i) \
;         __builtin_amdgcn_global_load_lds((const unsigned*)((const char*)(gbase) + (voff)[_i]), (PG8_LAS unsigned*)(lds + (bufoff) + ldsw + _i * 8192), 16, 0, 0); } while (0)
; #define PG8_LDA(dst, b, h) do { _Pragma("unroll") for (int m = 0; m < 4; ++m) _Pragma("unroll") for (int k = 0; k < 2; ++k) dst[m][k] = *(const PG8_LAS bf16x8*)(lds + PG8_SA(b, h) + aoff + m * 2048 + k * 1024); } while (0)
; #define PG8_LDB(dst, b, h) do { _Pragma("unroll") for (int n = 0; n < 2; ++n) _Pragma("unroll") for (int k = 0; k < 2; ++k) dst[n][k] = *(const PG8_LAS bf16x8*)(lds + PG8_SB(b, h) + boff + n * 2048 + k * 1024); } while (0)
; #define PG8_MMA(ai, bj, At, Bt) do { __builtin_amdgcn_s_setprio(1); _Pragma("unroll") for (int m = 0; m < 4; ++m) _Pragma("unroll") for (int n = 0; n < 2; ++n) _Pragma("unroll") for (int k = 0; k < 2; ++k) \
;         acc[ai][bj][m][n] = __builtin_amdgcn_mfma_f32_16x16x32_bf16(Bt[n][k], At[m][k], acc[ai][bj][m][n], 0, 0, 0); __builtin_amdgcn_s_setprio(0); } while (0)
; #define PG8_WAIT_V(n) asm volatile("s_waitcnt vmcnt(" #n ")" ::: "memory")
; #define PG8_WAIT_L(n) asm volatile("s_waitcnt lgkmcnt(" #n ")" ::: "memory")
; template <class Epi, class Sched, bool ALIGN_EPI = false, bool SP2 = false>
; __device__ __forceinline__ void gemm_phase(PG8_LAS unsigned char* lds, const Gemm g, const Sched& S, const Epi& E) {
;     ...
;             const bool last = (t == nt - 2);
;             const char* a1 = cA + (size_t)(t + 1) * kstep;
;             const char* a2 = last ? nA : cA + (size_t)(t + 2) * kstep; const char* b2 = last ? nB : cB + (size_t)(t + 2) * kstep;
;             const char* a3 = a2 + kstep; const char* b3 = b2 + kstep;
;             if (last && has_next) S.a_ready(nxt);
;             if constexpr (SP2) {
;             PG8_LDB(B0, 0, 0); PG8_LDB(B1, 0, 1); PG8_SCHED; PG8_LDA(At, 0, 0); PG8_STAGE(PG8_SA(1, 1), a1 + hstep, voffA);
;             PG8_WAIT_V(8); PG8_WAIT_L(0); PG8_BAR; PG8_MMA(0, 0, At, B0); PG8_MMA(0, 1, At, B1); PG8_BAR; PG8_SCHED;
;             PG8_LDA(At, 0, 1); PG8_STAGE(PG8_SB(0, 0), b2, voffB); PG8_STAGE(PG8_SB(0, 1), b2 + hstep, voffB); PG8_STAGE(PG8_SA(0, 0), a2, voffA);
;             PG8_WAIT_V(8); PG8_WAIT_L(0); PG8_BAR; PG8_MMA(1, 0, At, B0); PG8_MMA(1, 1, At, B1); PG8_BAR; PG8_SCHED;
.LBB0_573:
	v_add_u32_e32 v1, s74, v183
	ds_read_b128 v[132:135], v1
	ds_read_b128 v[136:139], v1 offset:1024
	ds_read_b128 v[140:143], v1 offset:2048
	ds_read_b128 v[144:147], v1 offset:3072
	v_add_u32_e32 v1, s75, v183
	ds_read_b128 v[148:151], v1
	ds_read_b128 v[152:155], v1 offset:1024
	ds_read_b128 v[156:159], v1 offset:2048
	ds_read_b128 v[160:163], v1 offset:3072
	s_add_u32 s50, s48, 0xfffe0080
	s_addc_u32 s51, s49, -1
	s_cmp_eq_u32 s84, 4
	s_cselect_b32 s53, s31, s51
	s_cselect_b32 s52, s39, s50
	s_cselect_b32 s51, s41, s83
	s_cselect_b32 s50, s47, s82
	s_add_i32 m0, s34, 0xc000
	ds_read_b128 v[186:189], v185
	ds_read_b128 v[190:193], v185 offset:1024
	ds_read_b128 v[194:197], v185 offset:2048
	ds_read_b128 v[198:201], v185 offset:3072
	ds_read_b128 v[202:205], v185 offset:4096
	ds_read_b128 v[206:209], v185 offset:5120
	ds_read_b128 v[210:213], v185 offset:6144
	ds_read_b128 v[214:217], v185 offset:7168
	global_load_lds_dwordx4 v174, s[48:49]
	s_add_i32 m0, s34, 0xe000
	s_nop 0
	global_load_lds_dwordx4 v176, s[48:49]
	s_waitcnt vmcnt(8)
	s_waitcnt lgkmcnt(0)
	s_barrier
	s_setprio 1
	s_waitcnt lgkmcnt(0)
	v_mfma_f32_16x16x32_bf16 v[128:131], v[132:135], v[186:189], v[128:131]
	v_mfma_f32_16x16x32_bf16 v[124:127], v[140:143], v[186:189], v[124:127]
	v_mfma_f32_16x16x32_bf16 v[120:123], v[132:135], v[194:197], v[120:123]
	v_mfma_f32_16x16x32_bf16 v[116:119], v[140:143], v[194:197], v[116:119]
	v_mfma_f32_16x16x32_bf16 v[112:115], v[132:135], v[202:205], v[112:115]
	v_mfma_f32_16x16x32_bf16 v[108:111], v[140:143], v[202:205], v[108:111]
	v_mfma_f32_16x16x32_bf16 v[104:107], v[132:135], v[210:213], v[104:107]
	v_mfma_f32_16x16x32_bf16 v[100:103], v[140:143], v[210:213], v[100:103]
	v_mfma_f32_16x16x32_bf16 v[128:131], v[136:139], v[190:193], v[128:131]
	v_mfma_f32_16x16x32_bf16 v[124:127], v[144:147], v[190:193], v[124:127]
	v_mfma_f32_16x16x32_bf16 v[120:123], v[136:139], v[198:201], v[120:123]
	v_mfma_f32_16x16x32_bf16 v[116:119], v[144:147], v[198:201], v[116:119]
	v_mfma_f32_16x16x32_bf16 v[112:115], v[136:139], v[206:209], v[112:115]
	v_mfma_f32_16x16x32_bf16 v[108:111], v[144:147], v[206:209], v[108:111]
	v_mfma_f32_16x16x32_bf16 v[104:107], v[136:139], v[214:217], v[104:107]
	v_mfma_f32_16x16x32_bf16 v[100:103], v[144:147], v[214:217], v[100:103]
	s_setprio 0
	s_setprio 1
	v_mfma_f32_16x16x32_bf16 v[96:99], v[148:151], v[186:189], v[96:99]
	v_mfma_f32_16x16x32_bf16 v[92:95], v[156:159], v[186:189], v[92:95]
	v_mfma_f32_16x16x32_bf16 v[88:91], v[148:151], v[194:197], v[88:91]
	v_mfma_f32_16x16x32_bf16 v[84:87], v[156:159], v[194:197], v[84:87]
	v_mfma_f32_16x16x32_bf16 v[80:83], v[148:151], v[202:205], v[80:83]
	v_mfma_f32_16x16x32_bf16 v[76:79], v[156:159], v[202:205], v[76:79]
	v_mfma_f32_16x16x32_bf16 v[72:75], v[148:151], v[210:213], v[72:75]
	v_mfma_f32_16x16x32_bf16 v[68:71], v[156:159], v[210:213], v[68:71]
	v_mfma_f32_16x16x32_bf16 v[96:99], v[152:155], v[190:193], v[96:99]
	v_mfma_f32_16x16x32_bf16 v[92:95], v[160:163], v[190:193], v[92:95]
	v_mfma_f32_16x16x32_bf16 v[88:91], v[152:155], v[198:201], v[88:91]
	v_mfma_f32_16x16x32_bf16 v[84:87], v[160:163], v[198:201], v[84:87]
	v_mfma_f32_16x16x32_bf16 v[80:83], v[152:155], v[206:209], v[80:83]
	v_mfma_f32_16x16x32_bf16 v[76:79], v[160:163], v[206:209], v[76:79]
	v_mfma_f32_16x16x32_bf16 v[72:75], v[152:155], v[214:217], v[72:75]
	v_mfma_f32_16x16x32_bf16 v[68:71], v[160:163], v[214:217], v[68:71]
	s_setprio 0
	s_barrier
	s_add_i32 s85, s74, s7
	s_mov_b32 m0, s85
	ds_read_b128 v[186:189], v185 offset:16384
	ds_read_b128 v[190:193], v185 offset:17408
	ds_read_b128 v[194:197], v185 offset:18432
	ds_read_b128 v[198:201], v185 offset:19456
	ds_read_b128 v[202:205], v185 offset:20480
	ds_read_b128 v[206:209], v185 offset:21504
	ds_read_b128 v[210:213], v185 offset:22528
	ds_read_b128 v[214:217], v185 offset:23552
	global_load_lds_dwordx4 v168, s[50:51]
	s_add_i32 m0, s85, 0x2000
	s_add_u32 s86, s50, 0x20000
	s_addc_u32 s87, s51, 0
	s_add_i32 s85, s75, s7
	global_load_lds_dwordx4 v172, s[50:51]
	s_mov_b32 m0, s85
	s_nop 0
	global_load_lds_dwordx4 v168, s[86:87]
	s_add_i32 m0, s85, 0x2000
	s_nop 0
	global_load_lds_dwordx4 v172, s[86:87]
	s_mov_b32 m0, s34
	s_nop 0
	global_load_lds_dwordx4 v166, s[52:53]
	s_mov_b32 m0, s35
	s_nop 0
	global_load_lds_dwordx4 v170, s[52:53]
	s_waitcnt vmcnt(8)
	s_waitcnt lgkmcnt(0)
	s_barrier
	s_setprio 1
	s_waitcnt lgkmcnt(0)
	v_mfma_f32_16x16x32_bf16 v[64:67], v[132:135], v[186:189], v[64:67]
	v_mfma_f32_16x16x32_bf16 v[60:63], v[140:143], v[186:189], v[60:63]
	v_mfma_f32_16x16x32_bf16 v[56:59], v[132:135], v[194:197], v[56:59]
	v_mfma_f32_16x16x32_bf16 v[52:55], v[140:143], v[194:197], v[52:55]
	v_mfma_f32_16x16x32_bf16 v[48:51], v[132:135], v[202:205], v[48:51]
	v_mfma_f32_16x16x32_bf16 v[44:47], v[140:143], v[202:205], v[44:47]
	v_mfma_f32_16x16x32_bf16 v[40:43], v[132:135], v[210:213], v[40:43]
	v_mfma_f32_16x16x32_bf16 v[36:39], v[140:143], v[210:213], v[36:39]
	v_mfma_f32_16x16x32_bf16 v[64:67], v[136:139], v[190:193], v[64:67]
	v_mfma_f32_16x16x32_bf16 v[60:63], v[144:147], v[190:193], v[60:63]
	v_mfma_f32_16x16x32_bf16 v[56:59], v[136:139], v[198:201], v[56:59]
	v_mfma_f32_16x16x32_bf16 v[52:55], v[144:147], v[198:201], v[52:55]
	v_mfma_f32_16x16x32_bf16 v[48:51], v[136:139], v[206:209], v[48:51]
	v_mfma_f32_16x16x32_bf16 v[44:47], v[144:147], v[206:209], v[44:47]
	v_mfma_f32_16x16x32_bf16 v[40:43], v[136:139], v[214:217], v[40:43]
	v_mfma_f32_16x16x32_bf16 v[36:39], v[144:147], v[214:217], v[36:39]
	s_setprio 0
	s_setprio 1
	v_mfma_f32_16x16x32_bf16 v[32:35], v[148:151], v[186:189], v[32:35]
	v_mfma_f32_16x16x32_bf16 v[28:31], v[156:159], v[186:189], v[28:31]
	v_mfma_f32_16x16x32_bf16 v[24:27], v[148:151], v[194:197], v[24:27]
	v_mfma_f32_16x16x32_bf16 v[20:23], v[156:159], v[194:197], v[20:23]
	v_mfma_f32_16x16x32_bf16 v[16:19], v[148:151], v[202:205], v[16:19]
	v_mfma_f32_16x16x32_bf16 v[12:15], v[156:159], v[202:205], v[12:15]
	v_mfma_f32_16x16x32_bf16 v[8:11], v[148:151], v[210:213], v[8:11]
	v_mfma_f32_16x16x32_bf16 v[2:5], v[156:159], v[210:213], v[4:7]
	v_mfma_f32_16x16x32_bf16 v[32:35], v[152:155], v[190:193], v[32:35]
	v_mfma_f32_16x16x32_bf16 v[28:31], v[160:163], v[190:193], v[28:31]
	v_mfma_f32_16x16x32_bf16 v[24:27], v[152:155], v[198:201], v[24:27]
	v_mfma_f32_16x16x32_bf16 v[20:23], v[160:163], v[198:201], v[20:23]
	v_mfma_f32_16x16x32_bf16 v[16:19], v[152:155], v[206:209], v[16:19]
	v_mfma_f32_16x16x32_bf16 v[12:15], v[160:163], v[206:209], v[12:15]
	v_mfma_f32_16x16x32_bf16 v[8:11], v[152:155], v[214:217], v[8:11]
	v_mfma_f32_16x16x32_bf16 v[2:5], v[160:163], v[214:217], v[2:5]
	s_setprio 0
	s_barrier
; #define PG8_STAGE(bufoff, gbase, voff) do { _Pragma("unroll") for (int _i = 0; _i < 2; ++_i) \
;         __builtin_amdgcn_global_load_lds((const unsigned*)((const char*)(gbase) + (voff)[_i]), (PG8_LAS unsigned*)(lds + (bufoff) + ldsw + _i * 8192), 16, 0, 0); } while (0)
; #define PG8_LDA(dst, b, h) do { _Pragma("unroll") for (int m = 0; m < 4; ++m) _Pragma("unroll") for (int k = 0; k < 2; ++k) dst[m][k] = *(const PG8_LAS bf16x8*)(lds + PG8_SA(b, h) + aoff + m * 2048 + k * 1024); } while (0)
; #define PG8_LDB(dst, b, h) do { _Pragma("unroll") for (int n = 0; n < 2; ++n) _Pragma("unroll") for (int k = 0; k < 2; ++k) dst[n][k] = *(const PG8_LAS bf16x8*)(lds + PG8_SB(b, h) + boff + n * 2048 + k * 1024); } while (0)
; #define PG8_MMA(ai, bj, At, Bt) do { __builtin_amdgcn_s_setprio(1); _Pragma("unroll") for (int m = 0; m < 4; ++m) _Pragma("unroll") for (int n = 0; n < 2; ++n) _Pragma("unroll") for (int k = 0; k < 2; ++k) \
;         acc[ai][bj][m][n] = __builtin_amdgcn_mfma_f32_16x16x32_bf16(Bt[n][k], At[m][k], acc[ai][bj][m][n], 0, 0, 0); __builtin_amdgcn_s_setprio(0); } while (0)
; #define PG8_WAIT_V(n) asm volatile("s_waitcnt vmcnt(" #n ")" ::: "memory")
; #define PG8_WAIT_L(n) asm volatile("s_waitcnt lgkmcnt(" #n ")" ::: "memory")
; #define PG8_BAR __builtin_amdgcn_s_barrier()
; #define PG8_SCHED __builtin_amdgcn_sched_barrier(0)
; template <class Epi, class Sched, bool ALIGN_EPI = false, bool SP2 = false>
; __device__ __forceinline__ void gemm_phase(PG8_LAS unsigned char* lds, const Gemm g, const Sched& S, const Epi& E) {
;     ...
;             PG8_LDB(B0, 1, 0); PG8_LDB(B1, 1, 1); PG8_SCHED; PG8_LDA(At, 1, 0); PG8_STAGE(PG8_SA(0, 1), a2 + hstep, voffA);
;             PG8_WAIT_V(8); PG8_WAIT_L(0); PG8_BAR; PG8_MMA(0, 0, At, B0); PG8_MMA(0, 1, At, B1); PG8_BAR; PG8_SCHED;
;             PG8_LDA(At, 1, 1); PG8_STAGE(PG8_SB(1, 0), b3, voffB); PG8_STAGE(PG8_SB(1, 1), b3 + hstep, voffB); PG8_STAGE(PG8_SA(1, 0), a3, voffA);
;             PG8_WAIT_V(8); PG8_WAIT_L(0); PG8_BAR; PG8_MMA(1, 0, At, B0); PG8_MMA(1, 1, At, B1); PG8_BAR; PG8_SCHED;
	s_add_i32 s85, 0, 0x18000
	v_add_u32_e32 v1, s85, v183
	s_add_i32 s86, 0, 0x1c000
	ds_read_b128 v[132:135], v1
	ds_read_b128 v[136:139], v1 offset:1024
	ds_read_b128 v[140:143], v1 offset:2048
	ds_read_b128 v[144:147], v1 offset:3072
	v_add_u32_e32 v1, s86, v183
	ds_read_b128 v[148:151], v1
	ds_read_b128 v[152:155], v1 offset:1024
	ds_read_b128 v[156:159], v1 offset:2048
	ds_read_b128 v[160:163], v1 offset:3072
	s_add_u32 s52, s52, 0x20000
	s_addc_u32 s53, s53, 0
	s_mov_b32 m0, s58
	ds_read_b128 v[186:189], v185 offset:32768
	ds_read_b128 v[190:193], v185 offset:33792
	ds_read_b128 v[194:197], v185 offset:34816
	ds_read_b128 v[198:201], v185 offset:35840
	ds_read_b128 v[202:205], v185 offset:36864
	ds_read_b128 v[206:209], v185 offset:37888
	ds_read_b128 v[210:213], v185 offset:38912
	ds_read_b128 v[214:217], v185 offset:39936
	global_load_lds_dwordx4 v166, s[52:53]
	s_mov_b32 m0, s59
	s_nop 0
	global_load_lds_dwordx4 v170, s[52:53]
	s_add_u32 s100, s50, 0x80
	s_addc_u32 s101, s51, 0
	s_sub_u32 s98, s52, 0x1ff80
	s_subb_u32 s99, s53, 0
	s_waitcnt vmcnt(8)
	s_waitcnt lgkmcnt(0)
	s_barrier
	s_setprio 1
	s_waitcnt lgkmcnt(0)
	v_mfma_f32_16x16x32_bf16 v[128:131], v[132:135], v[186:189], v[128:131]
	v_mfma_f32_16x16x32_bf16 v[124:127], v[140:143], v[186:189], v[124:127]
	v_mfma_f32_16x16x32_bf16 v[120:123], v[132:135], v[194:197], v[120:123]
	v_mfma_f32_16x16x32_bf16 v[116:119], v[140:143], v[194:197], v[116:119]
	v_mfma_f32_16x16x32_bf16 v[112:115], v[132:135], v[202:205], v[112:115]
	v_mfma_f32_16x16x32_bf16 v[108:111], v[140:143], v[202:205], v[108:111]
	v_mfma_f32_16x16x32_bf16 v[104:107], v[132:135], v[210:213], v[104:107]
	v_mfma_f32_16x16x32_bf16 v[100:103], v[140:143], v[210:213], v[100:103]
	v_mfma_f32_16x16x32_bf16 v[128:131], v[136:139], v[190:193], v[128:131]
	v_mfma_f32_16x16x32_bf16 v[124:127], v[144:147], v[190:193], v[124:127]
	v_mfma_f32_16x16x32_bf16 v[120:123], v[136:139], v[198:201], v[120:123]
	v_mfma_f32_16x16x32_bf16 v[116:119], v[144:147], v[198:201], v[116:119]
	v_mfma_f32_16x16x32_bf16 v[112:115], v[136:139], v[206:209], v[112:115]
	v_mfma_f32_16x16x32_bf16 v[108:111], v[144:147], v[206:209], v[108:111]
	v_mfma_f32_16x16x32_bf16 v[104:107], v[136:139], v[214:217], v[104:107]
	v_mfma_f32_16x16x32_bf16 v[100:103], v[144:147], v[214:217], v[100:103]
	s_setprio 0
	s_setprio 1
	v_mfma_f32_16x16x32_bf16 v[96:99], v[148:151], v[186:189], v[96:99]
	v_mfma_f32_16x16x32_bf16 v[92:95], v[156:159], v[186:189], v[92:95]
	v_mfma_f32_16x16x32_bf16 v[88:91], v[148:151], v[194:197], v[88:91]
	v_mfma_f32_16x16x32_bf16 v[84:87], v[156:159], v[194:197], v[84:87]
	v_mfma_f32_16x16x32_bf16 v[80:83], v[148:151], v[202:205], v[80:83]
	v_mfma_f32_16x16x32_bf16 v[76:79], v[156:159], v[202:205], v[76:79]
	v_mfma_f32_16x16x32_bf16 v[72:75], v[148:151], v[210:213], v[72:75]
	v_mfma_f32_16x16x32_bf16 v[68:71], v[156:159], v[210:213], v[68:71]
	v_mfma_f32_16x16x32_bf16 v[96:99], v[152:155], v[190:193], v[96:99]
	v_mfma_f32_16x16x32_bf16 v[92:95], v[160:163], v[190:193], v[92:95]
	v_mfma_f32_16x16x32_bf16 v[88:91], v[152:155], v[198:201], v[88:91]
	v_mfma_f32_16x16x32_bf16 v[84:87], v[160:163], v[198:201], v[84:87]
	v_mfma_f32_16x16x32_bf16 v[80:83], v[152:155], v[206:209], v[80:83]
	v_mfma_f32_16x16x32_bf16 v[76:79], v[160:163], v[206:209], v[76:79]
	v_mfma_f32_16x16x32_bf16 v[72:75], v[152:155], v[214:217], v[72:75]
	v_mfma_f32_16x16x32_bf16 v[68:71], v[160:163], v[214:217], v[68:71]
	s_setprio 0
	s_barrier
	s_add_i32 s52, s85, s7
	s_mov_b32 m0, s52
	ds_read_b128 v[186:189], v185 offset:49152
	ds_read_b128 v[190:193], v185 offset:50176
	ds_read_b128 v[194:197], v185 offset:51200
	ds_read_b128 v[198:201], v185 offset:52224
	ds_read_b128 v[202:205], v185 offset:53248
	ds_read_b128 v[206:209], v185 offset:54272
	ds_read_b128 v[210:213], v185 offset:55296
	ds_read_b128 v[214:217], v185 offset:56320
	global_load_lds_dwordx4 v168, s[100:101]
	s_add_i32 m0, s52, 0x2000
	s_add_u32 s50, s50, 0x20080
	s_addc_u32 s51, s51, 0
	s_add_i32 s52, s86, s7
	global_load_lds_dwordx4 v172, s[100:101]
	s_mov_b32 m0, s52
	s_nop 0
	global_load_lds_dwordx4 v168, s[50:51]
	s_add_i32 m0, s52, 0x2000
	s_nop 0
	global_load_lds_dwordx4 v172, s[50:51]
	s_mov_b32 m0, s72
	s_nop 0
	global_load_lds_dwordx4 v166, s[98:99]
	s_mov_b32 m0, s73
	s_nop 0
	global_load_lds_dwordx4 v170, s[98:99]
	s_waitcnt vmcnt(8)
	s_waitcnt lgkmcnt(0)
	s_barrier
	s_setprio 1
	s_waitcnt lgkmcnt(0)
	v_mfma_f32_16x16x32_bf16 v[64:67], v[132:135], v[186:189], v[64:67]
	v_mfma_f32_16x16x32_bf16 v[60:63], v[140:143], v[186:189], v[60:63]
	v_mfma_f32_16x16x32_bf16 v[56:59], v[132:135], v[194:197], v[56:59]
	v_mfma_f32_16x16x32_bf16 v[52:55], v[140:143], v[194:197], v[52:55]
	v_mfma_f32_16x16x32_bf16 v[48:51], v[132:135], v[202:205], v[48:51]
	v_mfma_f32_16x16x32_bf16 v[44:47], v[140:143], v[202:205], v[44:47]
	v_mfma_f32_16x16x32_bf16 v[40:43], v[132:135], v[210:213], v[40:43]
	v_mfma_f32_16x16x32_bf16 v[36:39], v[140:143], v[210:213], v[36:39]
	v_mfma_f32_16x16x32_bf16 v[64:67], v[136:139], v[190:193], v[64:67]
	v_mfma_f32_16x16x32_bf16 v[60:63], v[144:147], v[190:193], v[60:63]
	v_mfma_f32_16x16x32_bf16 v[56:59], v[136:139], v[198:201], v[56:59]
	v_mfma_f32_16x16x32_bf16 v[52:55], v[144:147], v[198:201], v[52:55]
	v_mfma_f32_16x16x32_bf16 v[48:51], v[136:139], v[206:209], v[48:51]
	v_mfma_f32_16x16x32_bf16 v[44:47], v[144:147], v[206:209], v[44:47]
	v_mfma_f32_16x16x32_bf16 v[40:43], v[136:139], v[214:217], v[40:43]
	v_mfma_f32_16x16x32_bf16 v[36:39], v[144:147], v[214:217], v[36:39]
	s_setprio 0
	s_setprio 1
	v_mfma_f32_16x16x32_bf16 v[32:35], v[148:151], v[186:189], v[32:35]
	v_mfma_f32_16x16x32_bf16 v[28:31], v[156:159], v[186:189], v[28:31]
	v_mfma_f32_16x16x32_bf16 v[24:27], v[148:151], v[194:197], v[24:27]
	v_mfma_f32_16x16x32_bf16 v[20:23], v[156:159], v[194:197], v[20:23]
	v_mfma_f32_16x16x32_bf16 v[16:19], v[148:151], v[202:205], v[16:19]
	v_mfma_f32_16x16x32_bf16 v[12:15], v[156:159], v[202:205], v[12:15]
	v_mfma_f32_16x16x32_bf16 v[6:9], v[148:151], v[210:213], v[8:11]
	v_mfma_f32_16x16x32_bf16 v[2:5], v[156:159], v[210:213], v[2:5]
	v_mfma_f32_16x16x32_bf16 v[32:35], v[152:155], v[190:193], v[32:35]
	v_mfma_f32_16x16x32_bf16 v[28:31], v[160:163], v[190:193], v[28:31]
	v_mfma_f32_16x16x32_bf16 v[24:27], v[152:155], v[198:201], v[24:27]
	v_mfma_f32_16x16x32_bf16 v[20:23], v[160:163], v[198:201], v[20:23]
	v_mfma_f32_16x16x32_bf16 v[16:19], v[152:155], v[206:209], v[16:19]
	v_mfma_f32_16x16x32_bf16 v[12:15], v[160:163], v[206:209], v[12:15]
	v_mfma_f32_16x16x32_bf16 v[8:11], v[152:155], v[214:217], v[6:9]
	v_mfma_f32_16x16x32_bf16 v[4:7], v[160:163], v[214:217], v[2:5]
	s_setprio 0
	s_barrier
	s_add_i32 s84, s84, 2
	s_add_u32 s48, s48, 0x100
	s_addc_u32 s49, s49, 0
	s_add_u32 s82, s82, 0x100
	s_addc_u32 s83, s83, 0
	s_cmp_gt_u32 s84, 5
	s_cbranch_scc0 .LBB0_573
	s_and_b64 vcc, exec, s[20:21]
	s_cbranch_vccz .LBB0_576
	s_barrier

; #define PG8_STAGE(bufoff, gbase, voff) do { _Pragma("unroll") for (int _i = 0; _i < 2; ++_i) \
;         __builtin_amdgcn_global_load_lds((const unsigned*)((const char*)(gbase) + (voff)[_i]), (PG8_LAS unsigned*)(lds + (bufoff) + ldsw + _i * 8192), 16, 0, 0); } while (0)
; #define PG8_LDA(dst, b, h) do { _Pragma("unroll") for (int m = 0; m < 4; ++m) _Pragma("unroll") for (int k = 0; k < 2; ++k) dst[m][k] = *(const PG8_LAS bf16x8*)(lds + PG8_SA(b, h) + aoff + m * 2048 + k * 1024); } while (0)
; #define PG8_LDB(dst, b, h) do { _Pragma("unroll") for (int n = 0; n < 2; ++n) _Pragma("unroll") for (int k = 0; k < 2; ++k) dst[n][k] = *(const PG8_LAS bf16x8*)(lds + PG8_SB(b, h) + boff + n * 2048 + k * 1024); } while (0)
; #define PG8_MMA(ai, bj, At, Bt) do { __builtin_amdgcn_s_setprio(1); _Pragma("unroll") for (int m = 0; m < 4; ++m) _Pragma("unroll") for (int n = 0; n < 2; ++n) _Pragma("unroll") for (int k = 0; k < 2; ++k) \
;         acc[ai][bj][m][n] = __builtin_amdgcn_mfma_f32_16x16x32_bf16(Bt[n][k], At[m][k], acc[ai][bj][m][n], 0, 0, 0); __builtin_amdgcn_s_setprio(0); } while (0)
; #define PG8_WAIT_V(n) asm volatile("s_waitcnt vmcnt(" #n ")" ::: "memory")
; #define PG8_WAIT_L(n) asm volatile("s_waitcnt lgkmcnt(" #n ")" ::: "memory")
; template <class Epi, class Sched, bool ALIGN_EPI = false, bool SP2 = false>
; __device__ __forceinline__ void gemm_phase(PG8_LAS unsigned char* lds, const Gemm g, const Sched& S, const Epi& E) {
;     ...
;             const bool last = (t == nt - 2);
;             const char* a1 = cA + (size_t)(t + 1) * kstep;
;             const char* a2 = last ? nA : cA + (size_t)(t + 2) * kstep; const char* b2 = last ? nB : cB + (size_t)(t + 2) * kstep;
;             const char* a3 = a2 + kstep; const char* b3 = b2 + kstep;
;             if (last && has_next) S.a_ready(nxt);
;             if constexpr (SP2) {
;             PG8_LDB(B0, 0, 0); PG8_LDB(B1, 0, 1); PG8_SCHED; PG8_LDA(At, 0, 0); PG8_STAGE(PG8_SA(1, 1), a1 + hstep, voffA);
;             PG8_WAIT_V(8); PG8_WAIT_L(0); PG8_BAR; PG8_MMA(0, 0, At, B0); PG8_MMA(0, 1, At, B1); PG8_BAR; PG8_SCHED;
;             PG8_LDA(At, 0, 1); PG8_STAGE(PG8_SB(0, 0), b2, voffB); PG8_STAGE(PG8_SB(0, 1), b2 + hstep, voffB); PG8_STAGE(PG8_SA(0, 0), a2, voffA);
;             PG8_WAIT_V(8); PG8_WAIT_L(0); PG8_BAR; PG8_MMA(1, 0, At, B0); PG8_MMA(1, 1, At, B1); PG8_BAR; PG8_SCHED;
.LBB0_680:
	ds_read_b128 v[128:131], v168
	ds_read_b128 v[150:153], v168 offset:1024
	ds_read_b128 v[154:157], v168 offset:2048
	ds_read_b128 v[172:175], v168 offset:3072
	ds_read_b128 v[176:179], v169
	ds_read_b128 v[180:183], v169 offset:1024
	ds_read_b128 v[184:187], v169 offset:2048
	ds_read_b128 v[188:191], v169 offset:3072
	s_add_u32 s31, s46, 0xfffc0080
	s_addc_u32 s48, s47, -1
	s_cmp_eq_u32 s30, 12
	s_cselect_b32 s51, s37, s48
	s_cselect_b32 s50, s72, s31
	s_cselect_b32 s49, s39, s3
	s_cselect_b32 s48, s73, s74
	s_add_i32 m0, s8, 0xc000
	ds_read_b128 v[192:195], v170
	ds_read_b128 v[196:199], v170 offset:1024
	ds_read_b128 v[200:203], v170 offset:2048
	ds_read_b128 v[204:207], v170 offset:3072
	ds_read_b128 v[208:211], v170 offset:4096
	ds_read_b128 v[212:215], v170 offset:5120
	ds_read_b128 v[216:219], v170 offset:6144
	ds_read_b128 v[220:223], v170 offset:7168
	global_load_lds_dwordx4 v142, s[46:47]
	s_add_i32 m0, s8, 0xe000
	s_nop 0
	global_load_lds_dwordx4 v144, s[46:47]
	s_waitcnt vmcnt(8)
	s_waitcnt lgkmcnt(0)
	s_barrier
	s_setprio 1
	s_waitcnt lgkmcnt(0)
	v_mfma_f32_16x16x32_bf16 v[124:127], v[128:131], v[192:195], v[124:127]
	v_mfma_f32_16x16x32_bf16 v[120:123], v[154:157], v[192:195], v[120:123]
	v_mfma_f32_16x16x32_bf16 v[108:111], v[128:131], v[200:203], v[108:111]
	v_mfma_f32_16x16x32_bf16 v[104:107], v[154:157], v[200:203], v[104:107]
	v_mfma_f32_16x16x32_bf16 v[92:95], v[128:131], v[208:211], v[92:95]
	v_mfma_f32_16x16x32_bf16 v[88:91], v[154:157], v[208:211], v[88:91]
	v_mfma_f32_16x16x32_bf16 v[76:79], v[128:131], v[216:219], v[76:79]
	v_mfma_f32_16x16x32_bf16 v[72:75], v[154:157], v[216:219], v[72:75]
	v_mfma_f32_16x16x32_bf16 v[124:127], v[150:153], v[196:199], v[124:127]
	v_mfma_f32_16x16x32_bf16 v[120:123], v[172:175], v[196:199], v[120:123]
	v_mfma_f32_16x16x32_bf16 v[108:111], v[150:153], v[204:207], v[108:111]
	v_mfma_f32_16x16x32_bf16 v[104:107], v[172:175], v[204:207], v[104:107]
	v_mfma_f32_16x16x32_bf16 v[92:95], v[150:153], v[212:215], v[92:95]
	v_mfma_f32_16x16x32_bf16 v[88:91], v[172:175], v[212:215], v[88:91]
	v_mfma_f32_16x16x32_bf16 v[76:79], v[150:153], v[220:223], v[76:79]
	v_mfma_f32_16x16x32_bf16 v[72:75], v[172:175], v[220:223], v[72:75]
	s_setprio 0
	s_setprio 1
	v_mfma_f32_16x16x32_bf16 v[116:119], v[176:179], v[192:195], v[116:119]
	v_mfma_f32_16x16x32_bf16 v[112:115], v[184:187], v[192:195], v[112:115]
	v_mfma_f32_16x16x32_bf16 v[100:103], v[176:179], v[200:203], v[100:103]
	v_mfma_f32_16x16x32_bf16 v[96:99], v[184:187], v[200:203], v[96:99]
	v_mfma_f32_16x16x32_bf16 v[84:87], v[176:179], v[208:211], v[84:87]
	v_mfma_f32_16x16x32_bf16 v[80:83], v[184:187], v[208:211], v[80:83]
	v_mfma_f32_16x16x32_bf16 v[68:71], v[176:179], v[216:219], v[68:71]
	v_mfma_f32_16x16x32_bf16 v[64:67], v[184:187], v[216:219], v[64:67]
	v_mfma_f32_16x16x32_bf16 v[116:119], v[180:183], v[196:199], v[116:119]
	v_mfma_f32_16x16x32_bf16 v[112:115], v[188:191], v[196:199], v[112:115]
	v_mfma_f32_16x16x32_bf16 v[100:103], v[180:183], v[204:207], v[100:103]
	v_mfma_f32_16x16x32_bf16 v[96:99], v[188:191], v[204:207], v[96:99]
	v_mfma_f32_16x16x32_bf16 v[84:87], v[180:183], v[212:215], v[84:87]
	v_mfma_f32_16x16x32_bf16 v[80:83], v[188:191], v[212:215], v[80:83]
	v_mfma_f32_16x16x32_bf16 v[68:71], v[180:183], v[220:223], v[68:71]
	v_mfma_f32_16x16x32_bf16 v[64:67], v[188:191], v[220:223], v[64:67]
	s_setprio 0
	s_barrier
	s_add_i32 s31, s58, s7
	s_mov_b32 m0, s31
	ds_read_b128 v[192:195], v170 offset:16384
	ds_read_b128 v[196:199], v170 offset:17408
	ds_read_b128 v[200:203], v170 offset:18432
	ds_read_b128 v[204:207], v170 offset:19456
	ds_read_b128 v[208:211], v170 offset:20480
	ds_read_b128 v[212:215], v170 offset:21504
	ds_read_b128 v[216:219], v170 offset:22528
	ds_read_b128 v[220:223], v170 offset:23552
	global_load_lds_dwordx4 v134, s[48:49]
	s_add_i32 m0, s31, 0x2000
	s_add_u32 s76, s48, 0x40000
	s_addc_u32 s77, s49, 0
	s_add_i32 s31, s59, s7
	global_load_lds_dwordx4 v138, s[48:49]
	s_mov_b32 m0, s31
	s_nop 0
	global_load_lds_dwordx4 v134, s[76:77]
	s_add_i32 m0, s31, 0x2000
	s_nop 0
	global_load_lds_dwordx4 v138, s[76:77]
	s_mov_b32 m0, s8
	s_nop 0
	global_load_lds_dwordx4 v132, s[50:51]
	s_mov_b32 m0, s9
	s_nop 0
	global_load_lds_dwordx4 v136, s[50:51]
	s_waitcnt vmcnt(8)
	s_waitcnt lgkmcnt(0)
	s_barrier
	s_setprio 1
	s_waitcnt lgkmcnt(0)
	v_mfma_f32_16x16x32_bf16 v[60:63], v[128:131], v[192:195], v[60:63]
	v_mfma_f32_16x16x32_bf16 v[56:59], v[154:157], v[192:195], v[56:59]
	v_mfma_f32_16x16x32_bf16 v[44:47], v[128:131], v[200:203], v[44:47]
	v_mfma_f32_16x16x32_bf16 v[40:43], v[154:157], v[200:203], v[40:43]
	v_mfma_f32_16x16x32_bf16 v[28:31], v[128:131], v[208:211], v[28:31]
	v_mfma_f32_16x16x32_bf16 v[24:27], v[154:157], v[208:211], v[24:27]
	v_mfma_f32_16x16x32_bf16 v[16:19], v[128:131], v[216:219], v[16:19]
	v_mfma_f32_16x16x32_bf16 v[8:11], v[154:157], v[216:219], v[8:11]
	v_mfma_f32_16x16x32_bf16 v[60:63], v[150:153], v[196:199], v[60:63]
	v_mfma_f32_16x16x32_bf16 v[56:59], v[172:175], v[196:199], v[56:59]
	v_mfma_f32_16x16x32_bf16 v[44:47], v[150:153], v[204:207], v[44:47]
	v_mfma_f32_16x16x32_bf16 v[40:43], v[172:175], v[204:207], v[40:43]
	v_mfma_f32_16x16x32_bf16 v[28:31], v[150:153], v[212:215], v[28:31]
	v_mfma_f32_16x16x32_bf16 v[24:27], v[172:175], v[212:215], v[24:27]
	v_mfma_f32_16x16x32_bf16 v[16:19], v[150:153], v[220:223], v[16:19]
	v_mfma_f32_16x16x32_bf16 v[8:11], v[172:175], v[220:223], v[8:11]
	s_setprio 0
	s_setprio 1
	v_mfma_f32_16x16x32_bf16 v[52:55], v[176:179], v[192:195], v[52:55]
	v_mfma_f32_16x16x32_bf16 v[48:51], v[184:187], v[192:195], v[48:51]
	v_mfma_f32_16x16x32_bf16 v[36:39], v[176:179], v[200:203], v[36:39]
	v_mfma_f32_16x16x32_bf16 v[32:35], v[184:187], v[200:203], v[32:35]
	v_mfma_f32_16x16x32_bf16 v[20:23], v[176:179], v[208:211], v[20:23]
	v_mfma_f32_16x16x32_bf16 v[12:15], v[184:187], v[208:211], v[12:15]
	v_mfma_f32_16x16x32_bf16 v[4:7], v[176:179], v[216:219], v[4:7]
	v_mfma_f32_16x16x32_bf16 v[0:3], v[184:187], v[216:219], v[0:3]
	v_mfma_f32_16x16x32_bf16 v[52:55], v[180:183], v[196:199], v[52:55]
	v_mfma_f32_16x16x32_bf16 v[48:51], v[188:191], v[196:199], v[48:51]
	v_mfma_f32_16x16x32_bf16 v[36:39], v[180:183], v[204:207], v[36:39]
	v_mfma_f32_16x16x32_bf16 v[32:35], v[188:191], v[204:207], v[32:35]
	v_mfma_f32_16x16x32_bf16 v[20:23], v[180:183], v[212:215], v[20:23]
	v_mfma_f32_16x16x32_bf16 v[12:15], v[188:191], v[212:215], v[12:15]
	v_mfma_f32_16x16x32_bf16 v[4:7], v[180:183], v[220:223], v[4:7]
	v_mfma_f32_16x16x32_bf16 v[0:3], v[188:191], v[220:223], v[0:3]
	s_setprio 0
	s_barrier
; #define PG8_STAGE(bufoff, gbase, voff) do { _Pragma("unroll") for (int _i = 0; _i < 2; ++_i) \
;         __builtin_amdgcn_global_load_lds((const unsigned*)((const char*)(gbase) + (voff)[_i]), (PG8_LAS unsigned*)(lds + (bufoff) + ldsw + _i * 8192), 16, 0, 0); } while (0)
; #define PG8_LDA(dst, b, h) do { _Pragma("unroll") for (int m = 0; m < 4; ++m) _Pragma("unroll") for (int k = 0; k < 2; ++k) dst[m][k] = *(const PG8_LAS bf16x8*)(lds + PG8_SA(b, h) + aoff + m * 2048 + k * 1024); } while (0)
; #define PG8_LDB(dst, b, h) do { _Pragma("unroll") for (int n = 0; n < 2; ++n) _Pragma("unroll") for (int k = 0; k < 2; ++k) dst[n][k] = *(const PG8_LAS bf16x8*)(lds + PG8_SB(b, h) + boff + n * 2048 + k * 1024); } while (0)
; #define PG8_MMA(ai, bj, At, Bt) do { __builtin_amdgcn_s_setprio(1); _Pragma("unroll") for (int m = 0; m < 4; ++m) _Pragma("unroll") for (int n = 0; n < 2; ++n) _Pragma("unroll") for (int k = 0; k < 2; ++k) \
;         acc[ai][bj][m][n] = __builtin_amdgcn_mfma_f32_16x16x32_bf16(Bt[n][k], At[m][k], acc[ai][bj][m][n], 0, 0, 0); __builtin_amdgcn_s_setprio(0); } while (0)
; #define PG8_WAIT_V(n) asm volatile("s_waitcnt vmcnt(" #n ")" ::: "memory")
; #define PG8_WAIT_L(n) asm volatile("s_waitcnt lgkmcnt(" #n ")" ::: "memory")
; #define PG8_BAR __builtin_amdgcn_s_barrier()
; #define PG8_SCHED __builtin_amdgcn_sched_barrier(0)
; template <class Epi, class Sched, bool ALIGN_EPI = false, bool SP2 = false>
; __device__ __forceinline__ void gemm_phase(PG8_LAS unsigned char* lds, const Gemm g, const Sched& S, const Epi& E) {
;     ...
;             PG8_LDB(B0, 1, 0); PG8_LDB(B1, 1, 1); PG8_SCHED; PG8_LDA(At, 1, 0); PG8_STAGE(PG8_SA(0, 1), a2 + hstep, voffA);
;             PG8_WAIT_V(8); PG8_WAIT_L(0); PG8_BAR; PG8_MMA(0, 0, At, B0); PG8_MMA(0, 1, At, B1); PG8_BAR; PG8_SCHED;
;             PG8_LDA(At, 1, 1); PG8_STAGE(PG8_SB(1, 0), b3, voffB); PG8_STAGE(PG8_SB(1, 1), b3 + hstep, voffB); PG8_STAGE(PG8_SA(1, 0), a3, voffA);
;             PG8_WAIT_V(8); PG8_WAIT_L(0); PG8_BAR; PG8_MMA(1, 0, At, B0); PG8_MMA(1, 1, At, B1); PG8_BAR; PG8_SCHED;
	s_add_i32 s31, 0, 0x18000
	v_add_u32_e32 v165, s31, v166
	s_add_i32 s75, 0, 0x1c000
	ds_read_b128 v[128:131], v165
	ds_read_b128 v[150:153], v165 offset:1024
	ds_read_b128 v[154:157], v165 offset:2048
	ds_read_b128 v[172:175], v165 offset:3072
	v_add_u32_e32 v165, s75, v166
	ds_read_b128 v[176:179], v165
	ds_read_b128 v[180:183], v165 offset:1024
	ds_read_b128 v[184:187], v165 offset:2048
	ds_read_b128 v[188:191], v165 offset:3072
	s_add_u32 s50, s50, 0x40000
	s_addc_u32 s51, s51, 0
	s_mov_b32 m0, s34
	ds_read_b128 v[192:195], v170 offset:32768
	ds_read_b128 v[196:199], v170 offset:33792
	ds_read_b128 v[200:203], v170 offset:34816
	ds_read_b128 v[204:207], v170 offset:35840
	ds_read_b128 v[208:211], v170 offset:36864
	ds_read_b128 v[212:215], v170 offset:37888
	ds_read_b128 v[216:219], v170 offset:38912
	ds_read_b128 v[220:223], v170 offset:39936
	global_load_lds_dwordx4 v132, s[50:51]
	s_mov_b32 m0, s35
	s_nop 0
	global_load_lds_dwordx4 v136, s[50:51]
	s_add_u32 s100, s48, 0x80
	s_addc_u32 s101, s49, 0
	s_sub_u32 s98, s50, 0x3ff80
	s_subb_u32 s99, s51, 0
	s_waitcnt vmcnt(8)
	s_waitcnt lgkmcnt(0)
	s_barrier
	s_setprio 1
	s_waitcnt lgkmcnt(0)
	v_mfma_f32_16x16x32_bf16 v[124:127], v[128:131], v[192:195], v[124:127]
	v_mfma_f32_16x16x32_bf16 v[120:123], v[154:157], v[192:195], v[120:123]
	v_mfma_f32_16x16x32_bf16 v[108:111], v[128:131], v[200:203], v[108:111]
	v_mfma_f32_16x16x32_bf16 v[104:107], v[154:157], v[200:203], v[104:107]
	v_mfma_f32_16x16x32_bf16 v[92:95], v[128:131], v[208:211], v[92:95]
	v_mfma_f32_16x16x32_bf16 v[88:91], v[154:157], v[208:211], v[88:91]
	v_mfma_f32_16x16x32_bf16 v[76:79], v[128:131], v[216:219], v[76:79]
	v_mfma_f32_16x16x32_bf16 v[72:75], v[154:157], v[216:219], v[72:75]
	v_mfma_f32_16x16x32_bf16 v[124:127], v[150:153], v[196:199], v[124:127]
	v_mfma_f32_16x16x32_bf16 v[120:123], v[172:175], v[196:199], v[120:123]
	v_mfma_f32_16x16x32_bf16 v[108:111], v[150:153], v[204:207], v[108:111]
	v_mfma_f32_16x16x32_bf16 v[104:107], v[172:175], v[204:207], v[104:107]
	v_mfma_f32_16x16x32_bf16 v[92:95], v[150:153], v[212:215], v[92:95]
	v_mfma_f32_16x16x32_bf16 v[88:91], v[172:175], v[212:215], v[88:91]
	v_mfma_f32_16x16x32_bf16 v[76:79], v[150:153], v[220:223], v[76:79]
	v_mfma_f32_16x16x32_bf16 v[72:75], v[172:175], v[220:223], v[72:75]
	s_setprio 0
	s_setprio 1
	v_mfma_f32_16x16x32_bf16 v[116:119], v[176:179], v[192:195], v[116:119]
	v_mfma_f32_16x16x32_bf16 v[112:115], v[184:187], v[192:195], v[112:115]
	v_mfma_f32_16x16x32_bf16 v[100:103], v[176:179], v[200:203], v[100:103]
	v_mfma_f32_16x16x32_bf16 v[96:99], v[184:187], v[200:203], v[96:99]
	v_mfma_f32_16x16x32_bf16 v[84:87], v[176:179], v[208:211], v[84:87]
	v_mfma_f32_16x16x32_bf16 v[80:83], v[184:187], v[208:211], v[80:83]
	v_mfma_f32_16x16x32_bf16 v[68:71], v[176:179], v[216:219], v[68:71]
	v_mfma_f32_16x16x32_bf16 v[64:67], v[184:187], v[216:219], v[64:67]
	v_mfma_f32_16x16x32_bf16 v[116:119], v[180:183], v[196:199], v[116:119]
	v_mfma_f32_16x16x32_bf16 v[112:115], v[188:191], v[196:199], v[112:115]
	v_mfma_f32_16x16x32_bf16 v[100:103], v[180:183], v[204:207], v[100:103]
	v_mfma_f32_16x16x32_bf16 v[96:99], v[188:191], v[204:207], v[96:99]
	v_mfma_f32_16x16x32_bf16 v[84:87], v[180:183], v[212:215], v[84:87]
	v_mfma_f32_16x16x32_bf16 v[80:83], v[188:191], v[212:215], v[80:83]
	v_mfma_f32_16x16x32_bf16 v[68:71], v[180:183], v[220:223], v[68:71]
	v_mfma_f32_16x16x32_bf16 v[64:67], v[188:191], v[220:223], v[64:67]
	s_setprio 0
	s_barrier
	s_add_i32 s31, s31, s7
	s_mov_b32 m0, s31
	ds_read_b128 v[192:195], v170 offset:49152
	ds_read_b128 v[196:199], v170 offset:50176
	ds_read_b128 v[200:203], v170 offset:51200
	ds_read_b128 v[204:207], v170 offset:52224
	ds_read_b128 v[208:211], v170 offset:53248
	ds_read_b128 v[212:215], v170 offset:54272
	ds_read_b128 v[216:219], v170 offset:55296
	ds_read_b128 v[220:223], v170 offset:56320
	global_load_lds_dwordx4 v134, s[100:101]
	s_add_i32 m0, s31, 0x2000
	s_add_u32 s48, s48, 0x40080
	s_addc_u32 s49, s49, 0
	s_add_i32 s31, s75, s7
	global_load_lds_dwordx4 v138, s[100:101]
	s_mov_b32 m0, s31
	s_nop 0
	global_load_lds_dwordx4 v134, s[48:49]
	s_add_i32 m0, s31, 0x2000
	s_nop 0
	global_load_lds_dwordx4 v138, s[48:49]
	s_mov_b32 m0, s53
	s_nop 0
	global_load_lds_dwordx4 v132, s[98:99]
	s_mov_b32 m0, s54
	s_nop 0
	global_load_lds_dwordx4 v136, s[98:99]
	s_waitcnt vmcnt(8)
	s_waitcnt lgkmcnt(0)
	s_barrier
	s_setprio 1
	s_waitcnt lgkmcnt(0)
	v_mfma_f32_16x16x32_bf16 v[60:63], v[128:131], v[192:195], v[60:63]
	v_mfma_f32_16x16x32_bf16 v[56:59], v[154:157], v[192:195], v[56:59]
	v_mfma_f32_16x16x32_bf16 v[44:47], v[128:131], v[200:203], v[44:47]
	v_mfma_f32_16x16x32_bf16 v[40:43], v[154:157], v[200:203], v[40:43]
	v_mfma_f32_16x16x32_bf16 v[28:31], v[128:131], v[208:211], v[28:31]
	v_mfma_f32_16x16x32_bf16 v[24:27], v[154:157], v[208:211], v[24:27]
	v_mfma_f32_16x16x32_bf16 v[16:19], v[128:131], v[216:219], v[16:19]
	v_mfma_f32_16x16x32_bf16 v[8:11], v[154:157], v[216:219], v[8:11]
	v_mfma_f32_16x16x32_bf16 v[60:63], v[150:153], v[196:199], v[60:63]
	v_mfma_f32_16x16x32_bf16 v[56:59], v[172:175], v[196:199], v[56:59]
	v_mfma_f32_16x16x32_bf16 v[44:47], v[150:153], v[204:207], v[44:47]
	v_mfma_f32_16x16x32_bf16 v[40:43], v[172:175], v[204:207], v[40:43]
	v_mfma_f32_16x16x32_bf16 v[28:31], v[150:153], v[212:215], v[28:31]
	v_mfma_f32_16x16x32_bf16 v[24:27], v[172:175], v[212:215], v[24:27]
	v_mfma_f32_16x16x32_bf16 v[16:19], v[150:153], v[220:223], v[16:19]
	v_mfma_f32_16x16x32_bf16 v[8:11], v[172:175], v[220:223], v[8:11]
	s_setprio 0
	s_setprio 1
	v_mfma_f32_16x16x32_bf16 v[52:55], v[176:179], v[192:195], v[52:55]
	v_mfma_f32_16x16x32_bf16 v[48:51], v[184:187], v[192:195], v[48:51]
	v_mfma_f32_16x16x32_bf16 v[36:39], v[176:179], v[200:203], v[36:39]
	v_mfma_f32_16x16x32_bf16 v[32:35], v[184:187], v[200:203], v[32:35]
	v_mfma_f32_16x16x32_bf16 v[20:23], v[176:179], v[208:211], v[20:23]
	v_mfma_f32_16x16x32_bf16 v[12:15], v[184:187], v[208:211], v[12:15]
	v_mfma_f32_16x16x32_bf16 v[4:7], v[176:179], v[216:219], v[4:7]
	v_mfma_f32_16x16x32_bf16 v[0:3], v[184:187], v[216:219], v[0:3]
	v_mfma_f32_16x16x32_bf16 v[52:55], v[180:183], v[196:199], v[52:55]
	v_mfma_f32_16x16x32_bf16 v[48:51], v[188:191], v[196:199], v[48:51]
	v_mfma_f32_16x16x32_bf16 v[36:39], v[180:183], v[204:207], v[36:39]
	v_mfma_f32_16x16x32_bf16 v[32:35], v[188:191], v[204:207], v[32:35]
	v_mfma_f32_16x16x32_bf16 v[20:23], v[180:183], v[212:215], v[20:23]
	v_mfma_f32_16x16x32_bf16 v[12:15], v[188:191], v[212:215], v[12:15]
	v_mfma_f32_16x16x32_bf16 v[4:7], v[180:183], v[220:223], v[4:7]
	v_mfma_f32_16x16x32_bf16 v[0:3], v[188:191], v[220:223], v[0:3]
	s_setprio 0
	s_barrier
	s_add_i32 s30, s30, 2
	s_add_u32 s46, s46, 0x100
	s_addc_u32 s47, s47, 0
	s_add_u32 s74, s74, 0x100
	s_addc_u32 s3, s3, 0
	s_cmp_gt_u32 s30, 13
	s_cbranch_scc0 .LBB0_680
	s_and_b64 vcc, exec, s[20:21]
	s_cbranch_vccz .LBB0_683
	s_barrier

; #define PG8_STAGE(bufoff, gbase, voff) do { _Pragma("unroll") for (int _i = 0; _i < 2; ++_i) \
;         __builtin_amdgcn_global_load_lds((const unsigned*)((const char*)(gbase) + (voff)[_i]), (PG8_LAS unsigned*)(lds + (bufoff) + ldsw + _i * 8192), 16, 0, 0); } while (0)
; #define PG8_LDA(dst, b, h) do { _Pragma("unroll") for (int m = 0; m < 4; ++m) _Pragma("unroll") for (int k = 0; k < 2; ++k) dst[m][k] = *(const PG8_LAS bf16x8*)(lds + PG8_SA(b, h) + aoff + m * 2048 + k * 1024); } while (0)
; #define PG8_LDB(dst, b, h) do { _Pragma("unroll") for (int n = 0; n < 2; ++n) _Pragma("unroll") for (int k = 0; k < 2; ++k) dst[n][k] = *(const PG8_LAS bf16x8*)(lds + PG8_SB(b, h) + boff + n * 2048 + k * 1024); } while (0)
; #define PG8_MMA(ai, bj, At, Bt) do { __builtin_amdgcn_s_setprio(1); _Pragma("unroll") for (int m = 0; m < 4; ++m) _Pragma("unroll") for (int n = 0; n < 2; ++n) _Pragma("unroll") for (int k = 0; k < 2; ++k) \
;         acc[ai][bj][m][n] = __builtin_amdgcn_mfma_f32_16x16x32_bf16(Bt[n][k], At[m][k], acc[ai][bj][m][n], 0, 0, 0); __builtin_amdgcn_s_setprio(0); } while (0)
; #define PG8_WAIT_V(n) asm volatile("s_waitcnt vmcnt(" #n ")" ::: "memory")
; #define PG8_WAIT_L(n) asm volatile("s_waitcnt lgkmcnt(" #n ")" ::: "memory")
; template <class Epi, class Sched, bool ALIGN_EPI = false, bool SP2 = false>
; __device__ __forceinline__ void gemm_phase(PG8_LAS unsigned char* lds, const Gemm g, const Sched& S, const Epi& E) {
;     ...
;             const bool last = (t == nt - 2);
;             const char* a1 = cA + (size_t)(t + 1) * kstep;
;             const char* a2 = last ? nA : cA + (size_t)(t + 2) * kstep; const char* b2 = last ? nB : cB + (size_t)(t + 2) * kstep;
;             const char* a3 = a2 + kstep; const char* b3 = b2 + kstep;
;             if (last && has_next) S.a_ready(nxt);
;             if constexpr (SP2) {
;             PG8_LDB(B0, 0, 0); PG8_LDB(B1, 0, 1); PG8_SCHED; PG8_LDA(At, 0, 0); PG8_STAGE(PG8_SA(1, 1), a1 + hstep, voffA);
;             PG8_WAIT_V(8); PG8_WAIT_L(0); PG8_BAR; PG8_MMA(0, 0, At, B0); PG8_MMA(0, 1, At, B1); PG8_BAR; PG8_SCHED;
;             PG8_LDA(At, 0, 1); PG8_STAGE(PG8_SB(0, 0), b2, voffB); PG8_STAGE(PG8_SB(0, 1), b2 + hstep, voffB); PG8_STAGE(PG8_SA(0, 0), a2, voffA);
;             PG8_WAIT_V(8); PG8_WAIT_L(0); PG8_BAR; PG8_MMA(1, 0, At, B0); PG8_MMA(1, 1, At, B1); PG8_BAR; PG8_SCHED;
.LBB0_771:
	ds_read_b128 v[144:147], v151
	ds_read_b128 v[156:159], v151 offset:1024
	ds_read_b128 v[160:163], v151 offset:2048
	ds_read_b128 v[166:169], v151 offset:3072
	ds_read_b128 v[170:173], v152
	ds_read_b128 v[174:177], v152 offset:1024
	ds_read_b128 v[178:181], v152 offset:2048
	ds_read_b128 v[182:185], v152 offset:3072
	s_add_u32 s31, s38, 0xfffc0080
	s_addc_u32 s40, s39, -1
	s_cmp_eq_u32 s30, 12
	s_cselect_b32 s43, s21, s40
	s_cselect_b32 s42, s53, s31
	s_cselect_b32 s41, s23, s3
	s_cselect_b32 s40, s54, s55
	s_add_i32 m0, s8, 0xc000
	ds_read_b128 v[186:189], v153
	ds_read_b128 v[190:193], v153 offset:1024
	ds_read_b128 v[194:197], v153 offset:2048
	ds_read_b128 v[198:201], v153 offset:3072
	ds_read_b128 v[202:205], v153 offset:4096
	ds_read_b128 v[206:209], v153 offset:5120
	ds_read_b128 v[210:213], v153 offset:6144
	ds_read_b128 v[214:217], v153 offset:7168
	global_load_lds_dwordx4 v136, s[38:39]
	s_add_i32 m0, s8, 0xe000
	s_nop 0
	global_load_lds_dwordx4 v138, s[38:39]
	s_waitcnt vmcnt(8)
	s_waitcnt lgkmcnt(0)
	s_barrier
	s_setprio 1
	s_waitcnt lgkmcnt(0)
	v_mfma_f32_16x16x32_bf16 v[124:127], v[144:147], v[186:189], v[124:127]
	v_mfma_f32_16x16x32_bf16 v[120:123], v[160:163], v[186:189], v[120:123]
	v_mfma_f32_16x16x32_bf16 v[116:119], v[144:147], v[194:197], v[116:119]
	v_mfma_f32_16x16x32_bf16 v[104:107], v[160:163], v[194:197], v[104:107]
	v_mfma_f32_16x16x32_bf16 v[92:95], v[144:147], v[202:205], v[92:95]
	v_mfma_f32_16x16x32_bf16 v[88:91], v[160:163], v[202:205], v[88:91]
	v_mfma_f32_16x16x32_bf16 v[76:79], v[144:147], v[210:213], v[76:79]
	v_mfma_f32_16x16x32_bf16 v[72:75], v[160:163], v[210:213], v[72:75]
	v_mfma_f32_16x16x32_bf16 v[124:127], v[156:159], v[190:193], v[124:127]
	v_mfma_f32_16x16x32_bf16 v[120:123], v[166:169], v[190:193], v[120:123]
	v_mfma_f32_16x16x32_bf16 v[116:119], v[156:159], v[198:201], v[116:119]
	v_mfma_f32_16x16x32_bf16 v[104:107], v[166:169], v[198:201], v[104:107]
	v_mfma_f32_16x16x32_bf16 v[92:95], v[156:159], v[206:209], v[92:95]
	v_mfma_f32_16x16x32_bf16 v[88:91], v[166:169], v[206:209], v[88:91]
	v_mfma_f32_16x16x32_bf16 v[76:79], v[156:159], v[214:217], v[76:79]
	v_mfma_f32_16x16x32_bf16 v[72:75], v[166:169], v[214:217], v[72:75]
	s_setprio 0
	s_setprio 1
	v_mfma_f32_16x16x32_bf16 v[112:115], v[170:173], v[186:189], v[112:115]
	v_mfma_f32_16x16x32_bf16 v[108:111], v[178:181], v[186:189], v[108:111]
	v_mfma_f32_16x16x32_bf16 v[100:103], v[170:173], v[194:197], v[100:103]
	v_mfma_f32_16x16x32_bf16 v[96:99], v[178:181], v[194:197], v[96:99]
	v_mfma_f32_16x16x32_bf16 v[84:87], v[170:173], v[202:205], v[84:87]
	v_mfma_f32_16x16x32_bf16 v[80:83], v[178:181], v[202:205], v[80:83]
	v_mfma_f32_16x16x32_bf16 v[68:71], v[170:173], v[210:213], v[68:71]
	v_mfma_f32_16x16x32_bf16 v[64:67], v[178:181], v[210:213], v[64:67]
	v_mfma_f32_16x16x32_bf16 v[112:115], v[174:177], v[190:193], v[112:115]
	v_mfma_f32_16x16x32_bf16 v[108:111], v[182:185], v[190:193], v[108:111]
	v_mfma_f32_16x16x32_bf16 v[100:103], v[174:177], v[198:201], v[100:103]
	v_mfma_f32_16x16x32_bf16 v[96:99], v[182:185], v[198:201], v[96:99]
	v_mfma_f32_16x16x32_bf16 v[84:87], v[174:177], v[206:209], v[84:87]
	v_mfma_f32_16x16x32_bf16 v[80:83], v[182:185], v[206:209], v[80:83]
	v_mfma_f32_16x16x32_bf16 v[68:71], v[174:177], v[214:217], v[68:71]
	v_mfma_f32_16x16x32_bf16 v[64:67], v[182:185], v[214:217], v[64:67]
	s_setprio 0
	s_barrier
	s_add_i32 s31, s49, s6
	s_mov_b32 m0, s31
	ds_read_b128 v[186:189], v153 offset:16384
	ds_read_b128 v[190:193], v153 offset:17408
	ds_read_b128 v[194:197], v153 offset:18432
	ds_read_b128 v[198:201], v153 offset:19456
	ds_read_b128 v[202:205], v153 offset:20480
	ds_read_b128 v[206:209], v153 offset:21504
	ds_read_b128 v[210:213], v153 offset:22528
	ds_read_b128 v[214:217], v153 offset:23552
	global_load_lds_dwordx4 v132, s[40:41]
	s_add_i32 m0, s31, 0x2000
	s_add_u32 s58, s40, 0x40000
	s_addc_u32 s59, s41, 0
	s_add_i32 s31, s50, s6
	global_load_lds_dwordx4 v128, s[40:41]
	s_mov_b32 m0, s31
	s_nop 0
	global_load_lds_dwordx4 v132, s[58:59]
	s_add_i32 m0, s31, 0x2000
	s_nop 0
	global_load_lds_dwordx4 v128, s[58:59]
	s_mov_b32 m0, s8
	s_nop 0
	global_load_lds_dwordx4 v134, s[42:43]
	s_mov_b32 m0, s9
	s_nop 0
	global_load_lds_dwordx4 v130, s[42:43]
	s_waitcnt vmcnt(8)
	s_waitcnt lgkmcnt(0)
	s_barrier
	s_setprio 1
	s_waitcnt lgkmcnt(0)
	v_mfma_f32_16x16x32_bf16 v[60:63], v[144:147], v[186:189], v[60:63]
	v_mfma_f32_16x16x32_bf16 v[56:59], v[160:163], v[186:189], v[56:59]
	v_mfma_f32_16x16x32_bf16 v[44:47], v[144:147], v[194:197], v[44:47]
	v_mfma_f32_16x16x32_bf16 v[40:43], v[160:163], v[194:197], v[40:43]
	v_mfma_f32_16x16x32_bf16 v[28:31], v[144:147], v[202:205], v[28:31]
	v_mfma_f32_16x16x32_bf16 v[24:27], v[160:163], v[202:205], v[24:27]
	v_mfma_f32_16x16x32_bf16 v[12:15], v[144:147], v[210:213], v[12:15]
	v_mfma_f32_16x16x32_bf16 v[8:11], v[160:163], v[210:213], v[8:11]
	v_mfma_f32_16x16x32_bf16 v[60:63], v[156:159], v[190:193], v[60:63]
	v_mfma_f32_16x16x32_bf16 v[56:59], v[166:169], v[190:193], v[56:59]
	v_mfma_f32_16x16x32_bf16 v[44:47], v[156:159], v[198:201], v[44:47]
	v_mfma_f32_16x16x32_bf16 v[40:43], v[166:169], v[198:201], v[40:43]
	v_mfma_f32_16x16x32_bf16 v[28:31], v[156:159], v[206:209], v[28:31]
	v_mfma_f32_16x16x32_bf16 v[24:27], v[166:169], v[206:209], v[24:27]
	v_mfma_f32_16x16x32_bf16 v[12:15], v[156:159], v[214:217], v[12:15]
	v_mfma_f32_16x16x32_bf16 v[8:11], v[166:169], v[214:217], v[8:11]
	s_setprio 0
	s_setprio 1
	v_mfma_f32_16x16x32_bf16 v[52:55], v[170:173], v[186:189], v[52:55]
	v_mfma_f32_16x16x32_bf16 v[48:51], v[178:181], v[186:189], v[48:51]
	v_mfma_f32_16x16x32_bf16 v[36:39], v[170:173], v[194:197], v[36:39]
	v_mfma_f32_16x16x32_bf16 v[32:35], v[178:181], v[194:197], v[32:35]
	v_mfma_f32_16x16x32_bf16 v[20:23], v[170:173], v[202:205], v[20:23]
	v_mfma_f32_16x16x32_bf16 v[16:19], v[178:181], v[202:205], v[16:19]
	v_mfma_f32_16x16x32_bf16 v[4:7], v[170:173], v[210:213], v[4:7]
	v_mfma_f32_16x16x32_bf16 v[0:3], v[178:181], v[210:213], v[0:3]
	v_mfma_f32_16x16x32_bf16 v[52:55], v[174:177], v[190:193], v[52:55]
	v_mfma_f32_16x16x32_bf16 v[48:51], v[182:185], v[190:193], v[48:51]
	v_mfma_f32_16x16x32_bf16 v[36:39], v[174:177], v[198:201], v[36:39]
	v_mfma_f32_16x16x32_bf16 v[32:35], v[182:185], v[198:201], v[32:35]
	v_mfma_f32_16x16x32_bf16 v[20:23], v[174:177], v[206:209], v[20:23]
	v_mfma_f32_16x16x32_bf16 v[16:19], v[182:185], v[206:209], v[16:19]
	v_mfma_f32_16x16x32_bf16 v[4:7], v[174:177], v[214:217], v[4:7]
	v_mfma_f32_16x16x32_bf16 v[0:3], v[182:185], v[214:217], v[0:3]
	s_setprio 0
	s_barrier
; #define PG8_STAGE(bufoff, gbase, voff) do { _Pragma("unroll") for (int _i = 0; _i < 2; ++_i) \
;         __builtin_amdgcn_global_load_lds((const unsigned*)((const char*)(gbase) + (voff)[_i]), (PG8_LAS unsigned*)(lds + (bufoff) + ldsw + _i * 8192), 16, 0, 0); } while (0)
; #define PG8_LDA(dst, b, h) do { _Pragma("unroll") for (int m = 0; m < 4; ++m) _Pragma("unroll") for (int k = 0; k < 2; ++k) dst[m][k] = *(const PG8_LAS bf16x8*)(lds + PG8_SA(b, h) + aoff + m * 2048 + k * 1024); } while (0)
; #define PG8_LDB(dst, b, h) do { _Pragma("unroll") for (int n = 0; n < 2; ++n) _Pragma("unroll") for (int k = 0; k < 2; ++k) dst[n][k] = *(const PG8_LAS bf16x8*)(lds + PG8_SB(b, h) + boff + n * 2048 + k * 1024); } while (0)
; #define PG8_MMA(ai, bj, At, Bt) do { __builtin_amdgcn_s_setprio(1); _Pragma("unroll") for (int m = 0; m < 4; ++m) _Pragma("unroll") for (int n = 0; n < 2; ++n) _Pragma("unroll") for (int k = 0; k < 2; ++k) \
;         acc[ai][bj][m][n] = __builtin_amdgcn_mfma_f32_16x16x32_bf16(Bt[n][k], At[m][k], acc[ai][bj][m][n], 0, 0, 0); __builtin_amdgcn_s_setprio(0); } while (0)
; #define PG8_WAIT_V(n) asm volatile("s_waitcnt vmcnt(" #n ")" ::: "memory")
; #define PG8_WAIT_L(n) asm volatile("s_waitcnt lgkmcnt(" #n ")" ::: "memory")
; #define PG8_BAR __builtin_amdgcn_s_barrier()
; #define PG8_SCHED __builtin_amdgcn_sched_barrier(0)
; template <class Epi, class Sched, bool ALIGN_EPI = false, bool SP2 = false>
; __device__ __forceinline__ void gemm_phase(PG8_LAS unsigned char* lds, const Gemm g, const Sched& S, const Epi& E) {
;     ...
;             PG8_LDB(B0, 1, 0); PG8_LDB(B1, 1, 1); PG8_SCHED; PG8_LDA(At, 1, 0); PG8_STAGE(PG8_SA(0, 1), a2 + hstep, voffA);
;             PG8_WAIT_V(8); PG8_WAIT_L(0); PG8_BAR; PG8_MMA(0, 0, At, B0); PG8_MMA(0, 1, At, B1); PG8_BAR; PG8_SCHED;
;             PG8_LDA(At, 1, 1); PG8_STAGE(PG8_SB(1, 0), b3, voffB); PG8_STAGE(PG8_SB(1, 1), b3 + hstep, voffB); PG8_STAGE(PG8_SA(1, 0), a3, voffA);
;             PG8_WAIT_V(8); PG8_WAIT_L(0); PG8_BAR; PG8_MMA(1, 0, At, B0); PG8_MMA(1, 1, At, B1); PG8_BAR; PG8_SCHED;
	s_add_i32 s31, 0, 0x18000
	v_add_u32_e32 v165, s31, v149
	s_add_i32 s58, 0, 0x1c000
	ds_read_b128 v[144:147], v165
	ds_read_b128 v[156:159], v165 offset:1024
	ds_read_b128 v[160:163], v165 offset:2048
	ds_read_b128 v[166:169], v165 offset:3072
	v_add_u32_e32 v165, s58, v149
	ds_read_b128 v[170:173], v165
	ds_read_b128 v[174:177], v165 offset:1024
	ds_read_b128 v[178:181], v165 offset:2048
	ds_read_b128 v[182:185], v165 offset:3072
	s_add_u32 s42, s42, 0x40000
	s_addc_u32 s43, s43, 0
	s_mov_b32 m0, s34
	ds_read_b128 v[186:189], v153 offset:32768
	ds_read_b128 v[190:193], v153 offset:33792
	ds_read_b128 v[194:197], v153 offset:34816
	ds_read_b128 v[198:201], v153 offset:35840
	ds_read_b128 v[202:205], v153 offset:36864
	ds_read_b128 v[206:209], v153 offset:37888
	ds_read_b128 v[210:213], v153 offset:38912
	ds_read_b128 v[214:217], v153 offset:39936
	global_load_lds_dwordx4 v134, s[42:43]
	s_mov_b32 m0, s35
	s_nop 0
	global_load_lds_dwordx4 v130, s[42:43]
	s_waitcnt vmcnt(8)
	s_waitcnt lgkmcnt(0)
	s_barrier
	s_setprio 1
	s_waitcnt lgkmcnt(0)
	v_mfma_f32_16x16x32_bf16 v[124:127], v[144:147], v[186:189], v[124:127]
	v_mfma_f32_16x16x32_bf16 v[120:123], v[160:163], v[186:189], v[120:123]
	v_mfma_f32_16x16x32_bf16 v[116:119], v[144:147], v[194:197], v[116:119]
	v_mfma_f32_16x16x32_bf16 v[104:107], v[160:163], v[194:197], v[104:107]
	v_mfma_f32_16x16x32_bf16 v[92:95], v[144:147], v[202:205], v[92:95]
	v_mfma_f32_16x16x32_bf16 v[88:91], v[160:163], v[202:205], v[88:91]
	v_mfma_f32_16x16x32_bf16 v[76:79], v[144:147], v[210:213], v[76:79]
	v_mfma_f32_16x16x32_bf16 v[72:75], v[160:163], v[210:213], v[72:75]
	v_mfma_f32_16x16x32_bf16 v[124:127], v[156:159], v[190:193], v[124:127]
	v_mfma_f32_16x16x32_bf16 v[120:123], v[166:169], v[190:193], v[120:123]
	v_mfma_f32_16x16x32_bf16 v[116:119], v[156:159], v[198:201], v[116:119]
	v_mfma_f32_16x16x32_bf16 v[104:107], v[166:169], v[198:201], v[104:107]
	v_mfma_f32_16x16x32_bf16 v[92:95], v[156:159], v[206:209], v[92:95]
	v_mfma_f32_16x16x32_bf16 v[88:91], v[166:169], v[206:209], v[88:91]
	v_mfma_f32_16x16x32_bf16 v[76:79], v[156:159], v[214:217], v[76:79]
	v_mfma_f32_16x16x32_bf16 v[72:75], v[166:169], v[214:217], v[72:75]
	s_setprio 0
	s_setprio 1
	v_mfma_f32_16x16x32_bf16 v[112:115], v[170:173], v[186:189], v[112:115]
	v_mfma_f32_16x16x32_bf16 v[108:111], v[178:181], v[186:189], v[108:111]
	v_mfma_f32_16x16x32_bf16 v[100:103], v[170:173], v[194:197], v[100:103]
	v_mfma_f32_16x16x32_bf16 v[96:99], v[178:181], v[194:197], v[96:99]
	v_mfma_f32_16x16x32_bf16 v[84:87], v[170:173], v[202:205], v[84:87]
	v_mfma_f32_16x16x32_bf16 v[80:83], v[178:181], v[202:205], v[80:83]
	v_mfma_f32_16x16x32_bf16 v[68:71], v[170:173], v[210:213], v[68:71]
	v_mfma_f32_16x16x32_bf16 v[64:67], v[178:181], v[210:213], v[64:67]
	v_mfma_f32_16x16x32_bf16 v[112:115], v[174:177], v[190:193], v[112:115]
	v_mfma_f32_16x16x32_bf16 v[108:111], v[182:185], v[190:193], v[108:111]
	v_mfma_f32_16x16x32_bf16 v[100:103], v[174:177], v[198:201], v[100:103]
	v_mfma_f32_16x16x32_bf16 v[96:99], v[182:185], v[198:201], v[96:99]
	v_mfma_f32_16x16x32_bf16 v[84:87], v[174:177], v[206:209], v[84:87]
	v_mfma_f32_16x16x32_bf16 v[80:83], v[182:185], v[206:209], v[80:83]
	v_mfma_f32_16x16x32_bf16 v[68:71], v[174:177], v[214:217], v[68:71]
	v_mfma_f32_16x16x32_bf16 v[64:67], v[182:185], v[214:217], v[64:67]
	s_setprio 0
	s_barrier
	s_add_i32 s31, s31, s6
	s_add_i32 m0, s31, 0xffffff80
	ds_read_b128 v[186:189], v153 offset:49152
	ds_read_b128 v[190:193], v153 offset:50176
	ds_read_b128 v[194:197], v153 offset:51200
	ds_read_b128 v[198:201], v153 offset:52224
	ds_read_b128 v[202:205], v153 offset:53248
	ds_read_b128 v[206:209], v153 offset:54272
	ds_read_b128 v[210:213], v153 offset:55296
	ds_read_b128 v[214:217], v153 offset:56320
	global_load_lds_dwordx4 v132, s[40:41] offset:128
	s_add_i32 m0, s31, 0x1f80
	s_add_i32 s31, s58, s6
	global_load_lds_dwordx4 v128, s[40:41] offset:128
	s_add_u32 s40, s40, 0x40080
	s_addc_u32 s41, s41, 0
	s_mov_b32 m0, s31
	s_nop 0
	global_load_lds_dwordx4 v132, s[40:41]
	s_add_i32 m0, s31, 0x2000
	s_nop 0
	global_load_lds_dwordx4 v128, s[40:41]
	s_sub_u32 s98, s42, 0x3ff80
	s_subb_u32 s99, s43, 0
	s_mov_b32 m0, s46
	s_nop 0
	global_load_lds_dwordx4 v134, s[98:99]
	s_mov_b32 m0, s47
	s_nop 0
	global_load_lds_dwordx4 v130, s[98:99]
	s_waitcnt vmcnt(8)
	s_waitcnt lgkmcnt(0)
	s_barrier
	s_setprio 1
	s_waitcnt lgkmcnt(0)
	v_mfma_f32_16x16x32_bf16 v[60:63], v[144:147], v[186:189], v[60:63]
	v_mfma_f32_16x16x32_bf16 v[56:59], v[160:163], v[186:189], v[56:59]
	v_mfma_f32_16x16x32_bf16 v[44:47], v[144:147], v[194:197], v[44:47]
	v_mfma_f32_16x16x32_bf16 v[40:43], v[160:163], v[194:197], v[40:43]
	v_mfma_f32_16x16x32_bf16 v[28:31], v[144:147], v[202:205], v[28:31]
	v_mfma_f32_16x16x32_bf16 v[24:27], v[160:163], v[202:205], v[24:27]
	v_mfma_f32_16x16x32_bf16 v[12:15], v[144:147], v[210:213], v[12:15]
	v_mfma_f32_16x16x32_bf16 v[8:11], v[160:163], v[210:213], v[8:11]
	v_mfma_f32_16x16x32_bf16 v[60:63], v[156:159], v[190:193], v[60:63]
	v_mfma_f32_16x16x32_bf16 v[56:59], v[166:169], v[190:193], v[56:59]
	v_mfma_f32_16x16x32_bf16 v[44:47], v[156:159], v[198:201], v[44:47]
	v_mfma_f32_16x16x32_bf16 v[40:43], v[166:169], v[198:201], v[40:43]
	v_mfma_f32_16x16x32_bf16 v[28:31], v[156:159], v[206:209], v[28:31]
	v_mfma_f32_16x16x32_bf16 v[24:27], v[166:169], v[206:209], v[24:27]
	v_mfma_f32_16x16x32_bf16 v[12:15], v[156:159], v[214:217], v[12:15]
	v_mfma_f32_16x16x32_bf16 v[8:11], v[166:169], v[214:217], v[8:11]
	s_setprio 0
	s_setprio 1
	v_mfma_f32_16x16x32_bf16 v[52:55], v[170:173], v[186:189], v[52:55]
	v_mfma_f32_16x16x32_bf16 v[48:51], v[178:181], v[186:189], v[48:51]
	v_mfma_f32_16x16x32_bf16 v[36:39], v[170:173], v[194:197], v[36:39]
	v_mfma_f32_16x16x32_bf16 v[32:35], v[178:181], v[194:197], v[32:35]
	v_mfma_f32_16x16x32_bf16 v[20:23], v[170:173], v[202:205], v[20:23]
	v_mfma_f32_16x16x32_bf16 v[16:19], v[178:181], v[202:205], v[16:19]
	v_mfma_f32_16x16x32_bf16 v[4:7], v[170:173], v[210:213], v[4:7]
	v_mfma_f32_16x16x32_bf16 v[0:3], v[178:181], v[210:213], v[0:3]
	v_mfma_f32_16x16x32_bf16 v[52:55], v[174:177], v[190:193], v[52:55]
	v_mfma_f32_16x16x32_bf16 v[48:51], v[182:185], v[190:193], v[48:51]
	v_mfma_f32_16x16x32_bf16 v[36:39], v[174:177], v[198:201], v[36:39]
	v_mfma_f32_16x16x32_bf16 v[32:35], v[182:185], v[198:201], v[32:35]
	v_mfma_f32_16x16x32_bf16 v[20:23], v[174:177], v[206:209], v[20:23]
	v_mfma_f32_16x16x32_bf16 v[16:19], v[182:185], v[206:209], v[16:19]
	v_mfma_f32_16x16x32_bf16 v[4:7], v[174:177], v[214:217], v[4:7]
	v_mfma_f32_16x16x32_bf16 v[0:3], v[182:185], v[214:217], v[0:3]
	s_setprio 0
	s_barrier
	s_add_i32 s30, s30, 2
	s_add_u32 s38, s38, 0x100
	s_addc_u32 s39, s39, 0
	s_add_u32 s55, s55, 0x100
	s_addc_u32 s3, s3, 0
	s_cmp_gt_u32 s30, 13
	s_cbranch_scc0 .LBB0_771
	s_and_b64 vcc, exec, s[18:19]
	s_cbranch_vccz .LBB0_774
	s_barrier

; #define PG8_STAGE(bufoff, gbase, voff) do { _Pragma("unroll") for (int _i = 0; _i < 2; ++_i) \
;         __builtin_amdgcn_global_load_lds((const unsigned*)((const char*)(gbase) + (voff)[_i]), (PG8_LAS unsigned*)(lds + (bufoff) + ldsw + _i * 8192), 16, 0, 0); } while (0)
; #define PG8_LDA(dst, b, h) do { _Pragma("unroll") for (int m = 0; m < 4; ++m) _Pragma("unroll") for (int k = 0; k < 2; ++k) dst[m][k] = *(const PG8_LAS bf16x8*)(lds + PG8_SA(b, h) + aoff + m * 2048 + k * 1024); } while (0)
; #define PG8_LDB(dst, b, h) do { _Pragma("unroll") for (int n = 0; n < 2; ++n) _Pragma("unroll") for (int k = 0; k < 2; ++k) dst[n][k] = *(const PG8_LAS bf16x8*)(lds + PG8_SB(b, h) + boff + n * 2048 + k * 1024); } while (0)
; #define PG8_MMA(ai, bj, At, Bt) do { __builtin_amdgcn_s_setprio(1); _Pragma("unroll") for (int m = 0; m < 4; ++m) _Pragma("unroll") for (int n = 0; n < 2; ++n) _Pragma("unroll") for (int k = 0; k < 2; ++k) \
;         acc[ai][bj][m][n] = __builtin_amdgcn_mfma_f32_16x16x32_bf16(Bt[n][k], At[m][k], acc[ai][bj][m][n], 0, 0, 0); __builtin_amdgcn_s_setprio(0); } while (0)
; #define PG8_WAIT_V(n) asm volatile("s_waitcnt vmcnt(" #n ")" ::: "memory")
; #define PG8_WAIT_L(n) asm volatile("s_waitcnt lgkmcnt(" #n ")" ::: "memory")
; template <class Epi, class Sched, bool ALIGN_EPI = false, bool SP2 = false>
; __device__ __forceinline__ void gemm_phase(PG8_LAS unsigned char* lds, const Gemm g, const Sched& S, const Epi& E) {
;     ...
;             const bool last = (t == nt - 2);
;             const char* a1 = cA + (size_t)(t + 1) * kstep;
;             const char* a2 = last ? nA : cA + (size_t)(t + 2) * kstep; const char* b2 = last ? nB : cB + (size_t)(t + 2) * kstep;
;             const char* a3 = a2 + kstep; const char* b3 = b2 + kstep;
;             if (last && has_next) S.a_ready(nxt);
;             if constexpr (SP2) {
;             PG8_LDB(B0, 0, 0); PG8_LDB(B1, 0, 1); PG8_SCHED; PG8_LDA(At, 0, 0); PG8_STAGE(PG8_SA(1, 1), a1 + hstep, voffA);
;             PG8_WAIT_V(8); PG8_WAIT_L(0); PG8_BAR; PG8_MMA(0, 0, At, B0); PG8_MMA(0, 1, At, B1); PG8_BAR; PG8_SCHED;
;             PG8_LDA(At, 0, 1); PG8_STAGE(PG8_SB(0, 0), b2, voffB); PG8_STAGE(PG8_SB(0, 1), b2 + hstep, voffB); PG8_STAGE(PG8_SA(0, 0), a2, voffA);
;             PG8_WAIT_V(8); PG8_WAIT_L(0); PG8_BAR; PG8_MMA(1, 0, At, B0); PG8_MMA(1, 1, At, B1); PG8_BAR; PG8_SCHED;
.LBB0_876:
	ds_read_b128 v[144:147], v153
	ds_read_b128 v[156:159], v153 offset:1024
	ds_read_b128 v[160:163], v153 offset:2048
	ds_read_b128 v[166:169], v153 offset:3072
	ds_read_b128 v[170:173], v154
	ds_read_b128 v[174:177], v154 offset:1024
	ds_read_b128 v[178:181], v154 offset:2048
	ds_read_b128 v[182:185], v154 offset:3072
	s_add_u32 s31, s34, 0xfff50080
	s_addc_u32 s36, s35, -1
	s_cmp_eq_u32 s30, 40
	s_cselect_b32 s39, s1, s36
	s_cselect_b32 s38, s0, s31
	s_cselect_b32 s37, s27, s54
	s_cselect_b32 s36, s26, s53
	s_add_i32 m0, s7, 0xc000
	ds_read_b128 v[186:189], v155
	ds_read_b128 v[190:193], v155 offset:1024
	ds_read_b128 v[194:197], v155 offset:2048
	ds_read_b128 v[198:201], v155 offset:3072
	ds_read_b128 v[202:205], v155 offset:4096
	ds_read_b128 v[206:209], v155 offset:5120
	ds_read_b128 v[210:213], v155 offset:6144
	ds_read_b128 v[214:217], v155 offset:7168
	global_load_lds_dwordx4 v136, s[34:35]
	s_add_i32 m0, s7, 0xe000
	s_nop 0
	global_load_lds_dwordx4 v138, s[34:35]
	s_waitcnt vmcnt(8)
	s_waitcnt lgkmcnt(0)
	s_barrier
	s_setprio 1
	s_waitcnt lgkmcnt(0)
	v_mfma_f32_16x16x32_bf16 v[124:127], v[144:147], v[186:189], v[124:127]
	v_mfma_f32_16x16x32_bf16 v[120:123], v[160:163], v[186:189], v[120:123]
	v_mfma_f32_16x16x32_bf16 v[112:115], v[144:147], v[194:197], v[112:115]
	v_mfma_f32_16x16x32_bf16 v[104:107], v[160:163], v[194:197], v[104:107]
	v_mfma_f32_16x16x32_bf16 v[96:99], v[144:147], v[202:205], v[96:99]
	v_mfma_f32_16x16x32_bf16 v[88:91], v[160:163], v[202:205], v[88:91]
	v_mfma_f32_16x16x32_bf16 v[80:83], v[144:147], v[210:213], v[80:83]
	v_mfma_f32_16x16x32_bf16 v[72:75], v[160:163], v[210:213], v[72:75]
	v_mfma_f32_16x16x32_bf16 v[124:127], v[156:159], v[190:193], v[124:127]
	v_mfma_f32_16x16x32_bf16 v[120:123], v[166:169], v[190:193], v[120:123]
	v_mfma_f32_16x16x32_bf16 v[112:115], v[156:159], v[198:201], v[112:115]
	v_mfma_f32_16x16x32_bf16 v[104:107], v[166:169], v[198:201], v[104:107]
	v_mfma_f32_16x16x32_bf16 v[96:99], v[156:159], v[206:209], v[96:99]
	v_mfma_f32_16x16x32_bf16 v[88:91], v[166:169], v[206:209], v[88:91]
	v_mfma_f32_16x16x32_bf16 v[80:83], v[156:159], v[214:217], v[80:83]
	v_mfma_f32_16x16x32_bf16 v[72:75], v[166:169], v[214:217], v[72:75]
	s_setprio 0
	s_setprio 1
	v_mfma_f32_16x16x32_bf16 v[116:119], v[170:173], v[186:189], v[116:119]
	v_mfma_f32_16x16x32_bf16 v[108:111], v[178:181], v[186:189], v[108:111]
	v_mfma_f32_16x16x32_bf16 v[100:103], v[170:173], v[194:197], v[100:103]
	v_mfma_f32_16x16x32_bf16 v[92:95], v[178:181], v[194:197], v[92:95]
	v_mfma_f32_16x16x32_bf16 v[84:87], v[170:173], v[202:205], v[84:87]
	v_mfma_f32_16x16x32_bf16 v[76:79], v[178:181], v[202:205], v[76:79]
	v_mfma_f32_16x16x32_bf16 v[68:71], v[170:173], v[210:213], v[68:71]
	v_mfma_f32_16x16x32_bf16 v[64:67], v[178:181], v[210:213], v[64:67]
	v_mfma_f32_16x16x32_bf16 v[116:119], v[174:177], v[190:193], v[116:119]
	v_mfma_f32_16x16x32_bf16 v[108:111], v[182:185], v[190:193], v[108:111]
	v_mfma_f32_16x16x32_bf16 v[100:103], v[174:177], v[198:201], v[100:103]
	v_mfma_f32_16x16x32_bf16 v[92:95], v[182:185], v[198:201], v[92:95]
	v_mfma_f32_16x16x32_bf16 v[84:87], v[174:177], v[206:209], v[84:87]
	v_mfma_f32_16x16x32_bf16 v[76:79], v[182:185], v[206:209], v[76:79]
	v_mfma_f32_16x16x32_bf16 v[68:71], v[174:177], v[214:217], v[68:71]
	v_mfma_f32_16x16x32_bf16 v[64:67], v[182:185], v[214:217], v[64:67]
	s_setprio 0
	s_barrier
	s_add_i32 s31, s47, s6
	s_mov_b32 m0, s31
	ds_read_b128 v[186:189], v155 offset:16384
	ds_read_b128 v[190:193], v155 offset:17408
	ds_read_b128 v[194:197], v155 offset:18432
	ds_read_b128 v[198:201], v155 offset:19456
	ds_read_b128 v[202:205], v155 offset:20480
	ds_read_b128 v[206:209], v155 offset:21504
	ds_read_b128 v[210:213], v155 offset:22528
	ds_read_b128 v[214:217], v155 offset:23552
	global_load_lds_dwordx4 v130, s[36:37]
	s_add_i32 m0, s31, 0x2000
	s_add_u32 s58, s36, 0xb0000
	s_addc_u32 s59, s37, 0
	s_add_i32 s31, s48, s6
	global_load_lds_dwordx4 v134, s[36:37]
	s_mov_b32 m0, s31
	s_nop 0
	global_load_lds_dwordx4 v130, s[58:59]
	s_add_i32 m0, s31, 0x2000
	s_nop 0
	global_load_lds_dwordx4 v134, s[58:59]
	s_mov_b32 m0, s7
	s_nop 0
	global_load_lds_dwordx4 v128, s[38:39]
	s_mov_b32 m0, s40
	s_nop 0
	global_load_lds_dwordx4 v132, s[38:39]
	s_waitcnt vmcnt(8)
	s_waitcnt lgkmcnt(0)
	s_barrier
	s_setprio 1
	s_waitcnt lgkmcnt(0)
	v_mfma_f32_16x16x32_bf16 v[60:63], v[144:147], v[186:189], v[60:63]
	v_mfma_f32_16x16x32_bf16 v[56:59], v[160:163], v[186:189], v[56:59]
	v_mfma_f32_16x16x32_bf16 v[48:51], v[144:147], v[194:197], v[48:51]
	v_mfma_f32_16x16x32_bf16 v[40:43], v[160:163], v[194:197], v[40:43]
	v_mfma_f32_16x16x32_bf16 v[32:35], v[144:147], v[202:205], v[32:35]
	v_mfma_f32_16x16x32_bf16 v[24:27], v[160:163], v[202:205], v[24:27]
	v_mfma_f32_16x16x32_bf16 v[16:19], v[144:147], v[210:213], v[16:19]
	v_mfma_f32_16x16x32_bf16 v[8:11], v[160:163], v[210:213], v[8:11]
	v_mfma_f32_16x16x32_bf16 v[60:63], v[156:159], v[190:193], v[60:63]
	v_mfma_f32_16x16x32_bf16 v[56:59], v[166:169], v[190:193], v[56:59]
	v_mfma_f32_16x16x32_bf16 v[48:51], v[156:159], v[198:201], v[48:51]
	v_mfma_f32_16x16x32_bf16 v[40:43], v[166:169], v[198:201], v[40:43]
	v_mfma_f32_16x16x32_bf16 v[32:35], v[156:159], v[206:209], v[32:35]
	v_mfma_f32_16x16x32_bf16 v[24:27], v[166:169], v[206:209], v[24:27]
	v_mfma_f32_16x16x32_bf16 v[16:19], v[156:159], v[214:217], v[16:19]
	v_mfma_f32_16x16x32_bf16 v[8:11], v[166:169], v[214:217], v[8:11]
	s_setprio 0
	s_setprio 1
	v_mfma_f32_16x16x32_bf16 v[52:55], v[170:173], v[186:189], v[52:55]
	v_mfma_f32_16x16x32_bf16 v[44:47], v[178:181], v[186:189], v[44:47]
	v_mfma_f32_16x16x32_bf16 v[36:39], v[170:173], v[194:197], v[36:39]
	v_mfma_f32_16x16x32_bf16 v[28:31], v[178:181], v[194:197], v[28:31]
	v_mfma_f32_16x16x32_bf16 v[20:23], v[170:173], v[202:205], v[20:23]
	v_mfma_f32_16x16x32_bf16 v[12:15], v[178:181], v[202:205], v[12:15]
	v_mfma_f32_16x16x32_bf16 v[4:7], v[170:173], v[210:213], v[4:7]
	v_mfma_f32_16x16x32_bf16 v[0:3], v[178:181], v[210:213], v[0:3]
	v_mfma_f32_16x16x32_bf16 v[52:55], v[174:177], v[190:193], v[52:55]
	v_mfma_f32_16x16x32_bf16 v[44:47], v[182:185], v[190:193], v[44:47]
	v_mfma_f32_16x16x32_bf16 v[36:39], v[174:177], v[198:201], v[36:39]
	v_mfma_f32_16x16x32_bf16 v[28:31], v[182:185], v[198:201], v[28:31]
	v_mfma_f32_16x16x32_bf16 v[20:23], v[174:177], v[206:209], v[20:23]
	v_mfma_f32_16x16x32_bf16 v[12:15], v[182:185], v[206:209], v[12:15]
	v_mfma_f32_16x16x32_bf16 v[4:7], v[174:177], v[214:217], v[4:7]
	v_mfma_f32_16x16x32_bf16 v[0:3], v[182:185], v[214:217], v[0:3]
	s_setprio 0
	s_barrier
; #define PG8_STAGE(bufoff, gbase, voff) do { _Pragma("unroll") for (int _i = 0; _i < 2; ++_i) \
;         __builtin_amdgcn_global_load_lds((const unsigned*)((const char*)(gbase) + (voff)[_i]), (PG8_LAS unsigned*)(lds + (bufoff) + ldsw + _i * 8192), 16, 0, 0); } while (0)
; #define PG8_LDA(dst, b, h) do { _Pragma("unroll") for (int m = 0; m < 4; ++m) _Pragma("unroll") for (int k = 0; k < 2; ++k) dst[m][k] = *(const PG8_LAS bf16x8*)(lds + PG8_SA(b, h) + aoff + m * 2048 + k * 1024); } while (0)
; #define PG8_LDB(dst, b, h) do { _Pragma("unroll") for (int n = 0; n < 2; ++n) _Pragma("unroll") for (int k = 0; k < 2; ++k) dst[n][k] = *(const PG8_LAS bf16x8*)(lds + PG8_SB(b, h) + boff + n * 2048 + k * 1024); } while (0)
; #define PG8_MMA(ai, bj, At, Bt) do { __builtin_amdgcn_s_setprio(1); _Pragma("unroll") for (int m = 0; m < 4; ++m) _Pragma("unroll") for (int n = 0; n < 2; ++n) _Pragma("unroll") for (int k = 0; k < 2; ++k) \
;         acc[ai][bj][m][n] = __builtin_amdgcn_mfma_f32_16x16x32_bf16(Bt[n][k], At[m][k], acc[ai][bj][m][n], 0, 0, 0); __builtin_amdgcn_s_setprio(0); } while (0)
; #define PG8_WAIT_V(n) asm volatile("s_waitcnt vmcnt(" #n ")" ::: "memory")
; #define PG8_WAIT_L(n) asm volatile("s_waitcnt lgkmcnt(" #n ")" ::: "memory")
; #define PG8_BAR __builtin_amdgcn_s_barrier()
; #define PG8_SCHED __builtin_amdgcn_sched_barrier(0)
; template <class Epi, class Sched, bool ALIGN_EPI = false, bool SP2 = false>
; __device__ __forceinline__ void gemm_phase(PG8_LAS unsigned char* lds, const Gemm g, const Sched& S, const Epi& E) {
;     ...
;             PG8_LDB(B0, 1, 0); PG8_LDB(B1, 1, 1); PG8_SCHED; PG8_LDA(At, 1, 0); PG8_STAGE(PG8_SA(0, 1), a2 + hstep, voffA);
;             PG8_WAIT_V(8); PG8_WAIT_L(0); PG8_BAR; PG8_MMA(0, 0, At, B0); PG8_MMA(0, 1, At, B1); PG8_BAR; PG8_SCHED;
;             PG8_LDA(At, 1, 1); PG8_STAGE(PG8_SB(1, 0), b3, voffB); PG8_STAGE(PG8_SB(1, 1), b3 + hstep, voffB); PG8_STAGE(PG8_SA(1, 0), a3, voffA);
;             PG8_WAIT_V(8); PG8_WAIT_L(0); PG8_BAR; PG8_MMA(1, 0, At, B0); PG8_MMA(1, 1, At, B1); PG8_BAR; PG8_SCHED;
	s_add_i32 s31, 0, 0x18000
	v_add_u32_e32 v165, s31, v151
	s_add_i32 s55, 0, 0x1c000
	ds_read_b128 v[144:147], v165
	ds_read_b128 v[156:159], v165 offset:1024
	ds_read_b128 v[160:163], v165 offset:2048
	ds_read_b128 v[166:169], v165 offset:3072
	v_add_u32_e32 v165, s55, v151
	ds_read_b128 v[170:173], v165
	ds_read_b128 v[174:177], v165 offset:1024
	ds_read_b128 v[178:181], v165 offset:2048
	ds_read_b128 v[182:185], v165 offset:3072
	s_add_u32 s38, s38, 0xb0000
	s_addc_u32 s39, s39, 0
	s_mov_b32 m0, s41
	ds_read_b128 v[186:189], v155 offset:32768
	ds_read_b128 v[190:193], v155 offset:33792
	ds_read_b128 v[194:197], v155 offset:34816
	ds_read_b128 v[198:201], v155 offset:35840
	ds_read_b128 v[202:205], v155 offset:36864
	ds_read_b128 v[206:209], v155 offset:37888
	ds_read_b128 v[210:213], v155 offset:38912
	ds_read_b128 v[214:217], v155 offset:39936
	global_load_lds_dwordx4 v128, s[38:39]
	s_mov_b32 m0, s42
	s_nop 0
	global_load_lds_dwordx4 v132, s[38:39]
	s_add_u32 s100, s36, 0x80
	s_addc_u32 s101, s37, 0
	s_sub_u32 s98, s38, 0xaff80
	s_subb_u32 s99, s39, 0
	s_waitcnt vmcnt(8)
	s_waitcnt lgkmcnt(0)
	s_barrier
	s_setprio 1
	s_waitcnt lgkmcnt(0)
	v_mfma_f32_16x16x32_bf16 v[124:127], v[144:147], v[186:189], v[124:127]
	v_mfma_f32_16x16x32_bf16 v[120:123], v[160:163], v[186:189], v[120:123]
	v_mfma_f32_16x16x32_bf16 v[112:115], v[144:147], v[194:197], v[112:115]
	v_mfma_f32_16x16x32_bf16 v[104:107], v[160:163], v[194:197], v[104:107]
	v_mfma_f32_16x16x32_bf16 v[96:99], v[144:147], v[202:205], v[96:99]
	v_mfma_f32_16x16x32_bf16 v[88:91], v[160:163], v[202:205], v[88:91]
	v_mfma_f32_16x16x32_bf16 v[80:83], v[144:147], v[210:213], v[80:83]
	v_mfma_f32_16x16x32_bf16 v[72:75], v[160:163], v[210:213], v[72:75]
	v_mfma_f32_16x16x32_bf16 v[124:127], v[156:159], v[190:193], v[124:127]
	v_mfma_f32_16x16x32_bf16 v[120:123], v[166:169], v[190:193], v[120:123]
	v_mfma_f32_16x16x32_bf16 v[112:115], v[156:159], v[198:201], v[112:115]
	v_mfma_f32_16x16x32_bf16 v[104:107], v[166:169], v[198:201], v[104:107]
	v_mfma_f32_16x16x32_bf16 v[96:99], v[156:159], v[206:209], v[96:99]
	v_mfma_f32_16x16x32_bf16 v[88:91], v[166:169], v[206:209], v[88:91]
	v_mfma_f32_16x16x32_bf16 v[80:83], v[156:159], v[214:217], v[80:83]
	v_mfma_f32_16x16x32_bf16 v[72:75], v[166:169], v[214:217], v[72:75]
	s_setprio 0
	s_setprio 1
	v_mfma_f32_16x16x32_bf16 v[116:119], v[170:173], v[186:189], v[116:119]
	v_mfma_f32_16x16x32_bf16 v[108:111], v[178:181], v[186:189], v[108:111]
	v_mfma_f32_16x16x32_bf16 v[100:103], v[170:173], v[194:197], v[100:103]
	v_mfma_f32_16x16x32_bf16 v[92:95], v[178:181], v[194:197], v[92:95]
	v_mfma_f32_16x16x32_bf16 v[84:87], v[170:173], v[202:205], v[84:87]
	v_mfma_f32_16x16x32_bf16 v[76:79], v[178:181], v[202:205], v[76:79]
	v_mfma_f32_16x16x32_bf16 v[68:71], v[170:173], v[210:213], v[68:71]
	v_mfma_f32_16x16x32_bf16 v[64:67], v[178:181], v[210:213], v[64:67]
	v_mfma_f32_16x16x32_bf16 v[116:119], v[174:177], v[190:193], v[116:119]
	v_mfma_f32_16x16x32_bf16 v[108:111], v[182:185], v[190:193], v[108:111]
	v_mfma_f32_16x16x32_bf16 v[100:103], v[174:177], v[198:201], v[100:103]
	v_mfma_f32_16x16x32_bf16 v[92:95], v[182:185], v[198:201], v[92:95]
	v_mfma_f32_16x16x32_bf16 v[84:87], v[174:177], v[206:209], v[84:87]
	v_mfma_f32_16x16x32_bf16 v[76:79], v[182:185], v[206:209], v[76:79]
	v_mfma_f32_16x16x32_bf16 v[68:71], v[174:177], v[214:217], v[68:71]
	v_mfma_f32_16x16x32_bf16 v[64:67], v[182:185], v[214:217], v[64:67]
	s_setprio 0
	s_barrier
	s_add_i32 s31, s31, s6
	s_mov_b32 m0, s31
	ds_read_b128 v[186:189], v155 offset:49152
	ds_read_b128 v[190:193], v155 offset:50176
	ds_read_b128 v[194:197], v155 offset:51200
	ds_read_b128 v[198:201], v155 offset:52224
	ds_read_b128 v[202:205], v155 offset:53248
	ds_read_b128 v[206:209], v155 offset:54272
	ds_read_b128 v[210:213], v155 offset:55296
	ds_read_b128 v[214:217], v155 offset:56320
	global_load_lds_dwordx4 v130, s[100:101]
	s_add_i32 m0, s31, 0x2000
	s_add_u32 s36, s36, 0xb0080
	s_addc_u32 s37, s37, 0
	s_add_i32 s31, s55, s6
	global_load_lds_dwordx4 v134, s[100:101]
	s_mov_b32 m0, s31
	s_nop 0
	global_load_lds_dwordx4 v130, s[36:37]
	s_add_i32 m0, s31, 0x2000
	s_nop 0
	global_load_lds_dwordx4 v134, s[36:37]
	s_mov_b32 m0, s44
	s_nop 0
	global_load_lds_dwordx4 v128, s[98:99]
	s_mov_b32 m0, s45
	s_nop 0
	global_load_lds_dwordx4 v132, s[98:99]
	s_waitcnt vmcnt(8)
	s_waitcnt lgkmcnt(0)
	s_barrier
	s_setprio 1
	s_waitcnt lgkmcnt(0)
	v_mfma_f32_16x16x32_bf16 v[60:63], v[144:147], v[186:189], v[60:63]
	v_mfma_f32_16x16x32_bf16 v[56:59], v[160:163], v[186:189], v[56:59]
	v_mfma_f32_16x16x32_bf16 v[48:51], v[144:147], v[194:197], v[48:51]
	v_mfma_f32_16x16x32_bf16 v[40:43], v[160:163], v[194:197], v[40:43]
	v_mfma_f32_16x16x32_bf16 v[32:35], v[144:147], v[202:205], v[32:35]
	v_mfma_f32_16x16x32_bf16 v[24:27], v[160:163], v[202:205], v[24:27]
	v_mfma_f32_16x16x32_bf16 v[16:19], v[144:147], v[210:213], v[16:19]
	v_mfma_f32_16x16x32_bf16 v[8:11], v[160:163], v[210:213], v[8:11]
	v_mfma_f32_16x16x32_bf16 v[60:63], v[156:159], v[190:193], v[60:63]
	v_mfma_f32_16x16x32_bf16 v[56:59], v[166:169], v[190:193], v[56:59]
	v_mfma_f32_16x16x32_bf16 v[48:51], v[156:159], v[198:201], v[48:51]
	v_mfma_f32_16x16x32_bf16 v[40:43], v[166:169], v[198:201], v[40:43]
	v_mfma_f32_16x16x32_bf16 v[32:35], v[156:159], v[206:209], v[32:35]
	v_mfma_f32_16x16x32_bf16 v[24:27], v[166:169], v[206:209], v[24:27]
	v_mfma_f32_16x16x32_bf16 v[16:19], v[156:159], v[214:217], v[16:19]
	v_mfma_f32_16x16x32_bf16 v[8:11], v[166:169], v[214:217], v[8:11]
	s_setprio 0
	s_setprio 1
	v_mfma_f32_16x16x32_bf16 v[52:55], v[170:173], v[186:189], v[52:55]
	v_mfma_f32_16x16x32_bf16 v[44:47], v[178:181], v[186:189], v[44:47]
	v_mfma_f32_16x16x32_bf16 v[36:39], v[170:173], v[194:197], v[36:39]
	v_mfma_f32_16x16x32_bf16 v[28:31], v[178:181], v[194:197], v[28:31]
	v_mfma_f32_16x16x32_bf16 v[20:23], v[170:173], v[202:205], v[20:23]
	v_mfma_f32_16x16x32_bf16 v[12:15], v[178:181], v[202:205], v[12:15]
	v_mfma_f32_16x16x32_bf16 v[4:7], v[170:173], v[210:213], v[4:7]
	v_mfma_f32_16x16x32_bf16 v[0:3], v[178:181], v[210:213], v[0:3]
	v_mfma_f32_16x16x32_bf16 v[52:55], v[174:177], v[190:193], v[52:55]
	v_mfma_f32_16x16x32_bf16 v[44:47], v[182:185], v[190:193], v[44:47]
	v_mfma_f32_16x16x32_bf16 v[36:39], v[174:177], v[198:201], v[36:39]
	v_mfma_f32_16x16x32_bf16 v[28:31], v[182:185], v[198:201], v[28:31]
	v_mfma_f32_16x16x32_bf16 v[20:23], v[174:177], v[206:209], v[20:23]
	v_mfma_f32_16x16x32_bf16 v[12:15], v[182:185], v[206:209], v[12:15]
	v_mfma_f32_16x16x32_bf16 v[4:7], v[174:177], v[214:217], v[4:7]
	v_mfma_f32_16x16x32_bf16 v[0:3], v[182:185], v[214:217], v[0:3]
	s_setprio 0
	s_barrier
	s_add_i32 s30, s30, 2
	s_add_u32 s34, s34, 0x100
	s_addc_u32 s35, s35, 0
	s_add_u32 s53, s53, 0x100
	s_addc_u32 s54, s54, 0
	s_cmp_gt_u32 s30, 41
	s_cbranch_scc0 .LBB0_876
	s_and_b64 vcc, exec, s[16:17]
	s_cbranch_vccz .LBB0_879
	s_barrier

; __global__ void __launch_bounds__(NWAVES * 64, 2) hybrid_fwd(Args args) {
	.amdhsa_kernel _Z10hybrid_fwd4Args
		.amdhsa_group_segment_fixed_size 0
		.amdhsa_private_segment_fixed_size 0
		.amdhsa_kernarg_size 424
		.amdhsa_user_sgpr_count 2
		.amdhsa_user_sgpr_dispatch_ptr 0
		.amdhsa_user_sgpr_queue_ptr 0
		.amdhsa_user_sgpr_kernarg_segment_ptr 1
		.amdhsa_user_sgpr_dispatch_id 0
		.amdhsa_user_sgpr_kernarg_preload_length 0
		.amdhsa_user_sgpr_kernarg_preload_offset 0
		.amdhsa_user_sgpr_private_segment_size 0
		.amdhsa_uses_dynamic_stack 0
		.amdhsa_enable_private_segment 0
		.amdhsa_system_sgpr_workgroup_id_x 1
		.amdhsa_system_sgpr_workgroup_id_y 0
		.amdhsa_system_sgpr_workgroup_id_z 0
		.amdhsa_system_sgpr_workgroup_info 0
		.amdhsa_system_vgpr_workitem_id 2
		.amdhsa_next_free_vgpr 256
		.amdhsa_next_free_sgpr 102
		.amdhsa_accum_offset 256
		.amdhsa_reserve_vcc 1
		.amdhsa_float_round_mode_32 0
		.amdhsa_float_round_mode_16_64 0
		.amdhsa_float_denorm_mode_32 3
		.amdhsa_float_denorm_mode_16_64 3
		.amdhsa_dx10_clamp 1
		.amdhsa_ieee_mode 1
		.amdhsa_fp16_overflow 0
		.amdhsa_tg_split 0
		.amdhsa_exception_fp_ieee_invalid_op 0
		.amdhsa_exception_fp_denorm_src 0
		.amdhsa_exception_fp_ieee_div_zero 0
		.amdhsa_exception_fp_ieee_overflow 0
		.amdhsa_exception_fp_ieee_underflow 0
		.amdhsa_exception_fp_ieee_inexact 0
		.amdhsa_exception_int_div_zero 0
	.end_amdhsa_kernel

; __global__ void __launch_bounds__(NWAVES * 64, 2) hybrid_fwd(Args args) {
amdhsa.kernels:
  - .agpr_count:     0
    .args:
      - .offset:         0
        .size:           168
        .value_kind:     by_value
      - .offset:         168
        .size:           4
        .value_kind:     hidden_block_count_x
      - .offset:         172
        .size:           4
        .value_kind:     hidden_block_count_y
      - .offset:         176
        .size:           4
        .value_kind:     hidden_block_count_z
      - .offset:         180
        .size:           2
        .value_kind:     hidden_group_size_x
      - .offset:         182
        .size:           2
        .value_kind:     hidden_group_size_y
      - .offset:         184
        .size:           2
        .value_kind:     hidden_group_size_z
      - .offset:         186
        .size:           2
        .value_kind:     hidden_remainder_x
      - .offset:         188
        .size:           2
        .value_kind:     hidden_remainder_y
      - .offset:         190
        .size:           2
        .value_kind:     hidden_remainder_z
      - .offset:         208
        .size:           8
        .value_kind:     hidden_global_offset_x
      - .offset:         216
        .size:           8
        .value_kind:     hidden_global_offset_y
      - .offset:         224
        .size:           8
        .value_kind:     hidden_global_offset_z
      - .offset:         232
        .size:           2
        .value_kind:     hidden_grid_dims
      - .offset:         256
        .size:           8
        .value_kind:     hidden_multigrid_sync_arg
      - .offset:         288
        .size:           4
        .value_kind:     hidden_dynamic_lds_size
    .group_segment_fixed_size: 0
    .kernarg_segment_align: 8
    .kernarg_segment_size: 424
    .language:       OpenCL C
    .language_version:
      - 2
      - 0
    .max_flat_workgroup_size: 512
    .name:           _Z10hybrid_fwd4Args
    .private_segment_fixed_size: 0
    .sgpr_count:     108
    .sgpr_spill_count: 13
    .symbol:         _Z10hybrid_fwd4Args.kd
    .uniform_work_group_size: 1
    .uses_dynamic_stack: false
    .vgpr_count:     256
    .vgpr_spill_count: 0
    .wavefront_size: 64
